# fused-norm epilogues (4 phases): second column half's gain/scale/shift vectors loaded together with the first half's instead of after the first half's stores (one fewer round trip and no wait behind t
# baseline (speedup 1.0000x reference)
.LBB0_374:
	s_or_b64 exec, exec, s[68:69]
	s_add_u32 s0, s54, s70
	s_addc_u32 s1, s55, s71
	v_lshlrev_b64 v[0:1], 2, v[178:179]
	v_lshl_add_u64 v[4:5], s[0:1], 0, v[0:1]
	s_mov_b64 s[0:1], 0x4000
	v_lshl_add_u64 v[120:121], v[4:5], 0, s[0:1]
	s_movk_i32 s0, 0x4000
	v_lshl_add_u64 v[114:115], s[14:15], 0, v[0:1]
	v_add_co_u32_e32 v0, vcc, s0, v4
	s_waitcnt vmcnt(0) lgkmcnt(0)
	s_barrier
	s_nop 0
	v_addc_co_u32_e32 v1, vcc, 0, v5, vcc
	s_movk_i32 s18, 0x3000
	flat_load_dwordx4 v[12:15], v[114:115]
	flat_load_dwordx4 v[8:11], v[114:115] offset:16
	global_load_dwordx4 v[16:19], v[0:1], off
	global_load_dwordx4 v[20:23], v[120:121], off offset:16
	s_mov_b64 s[0:1], 0x3000
	v_add_co_u32_e32 v0, vcc, s18, v4
	v_lshl_add_u64 v[122:123], v[4:5], 0, s[0:1]
	s_nop 0
	v_addc_co_u32_e32 v1, vcc, 0, v5, vcc
	global_load_dwordx4 v[0:3], v[0:1], off
	ds_read_b32 v182, v206
	global_load_dwordx4 v[4:7], v[122:123], off offset:16
	global_load_dwordx4 v[228:231], v[120:121], off offset:512
	global_load_dwordx4 v[232:235], v[120:121], off offset:528
	global_load_dwordx4 v[236:239], v[114:115], off offset:512
	global_load_dwordx4 v[240:243], v[114:115], off offset:528
	global_load_dwordx4 v[248:251], v[122:123], off offset:512
	global_load_dwordx4 v[252:255], v[122:123], off offset:528
	v_lshl_add_u64 v[168:169], s[46:47], 0, v[168:169]
	v_lshl_add_u64 v[168:169], v[168:169], 0, v[112:113]
	v_add_u32_e32 v180, s35, v198
	s_waitcnt lgkmcnt(0)
	v_pk_mul_f32 v[142:143], v[142:143], v[182:183] op_sel_hi:[1,0]
	v_pk_mul_f32 v[140:141], v[140:141], v[182:183] op_sel_hi:[1,0]
	v_pk_mul_f32 v[138:139], v[138:139], v[182:183] op_sel_hi:[1,0]
	v_pk_mul_f32 v[136:137], v[136:137], v[182:183] op_sel_hi:[1,0]
	v_ashrrev_i32_e32 v181, 31, v180
	v_add_u32_e32 v184, s35, v199
	v_ashrrev_i32_e32 v185, 31, v184
	v_add_u32_e32 v178, s35, v200
	v_ashrrev_i32_e32 v179, 31, v178
	s_andn2_b64 vcc, exec, s[10:11]
	s_mov_b64 s[0:1], -1
	s_waitcnt vmcnt(0)
	v_pk_add_f32 v[18:19], v[18:19], 1.0 op_sel_hi:[1,0]
	v_pk_add_f32 v[16:17], v[16:17], 1.0 op_sel_hi:[1,0]
	v_pk_add_f32 v[22:23], v[22:23], 1.0 op_sel_hi:[1,0]
	v_pk_add_f32 v[182:183], v[20:21], 1.0 op_sel_hi:[1,0]
	v_pk_mul_f32 v[18:19], v[14:15], v[18:19]
	v_pk_mul_f32 v[20:21], v[12:13], v[16:17]
	v_pk_mul_f32 v[14:15], v[10:11], v[22:23]
	v_pk_mul_f32 v[16:17], v[8:9], v[182:183]
	v_pk_fma_f32 v[10:11], v[18:19], v[142:143], v[2:3]
	v_pk_fma_f32 v[8:9], v[20:21], v[140:141], v[0:1]
	v_pk_fma_f32 v[12:13], v[14:15], v[138:139], v[6:7]
	v_pk_fma_f32 v[22:23], v[16:17], v[136:137], v[4:5]
	v_cvt_pk_bf16_f32 v8, v8, v9
	v_cvt_pk_bf16_f32 v9, v10, v11
	s_nop 0
	v_cvt_pk_bf16_f32 v10, v22, v23
	v_cvt_pk_bf16_f32 v11, v12, v13
	ds_read_b32 v12, v207
	global_store_dwordx4 v[168:169], v[8:11], off
	s_waitcnt lgkmcnt(0)
	v_pk_mul_f32 v[22:23], v[148:149], v[12:13] op_sel_hi:[1,0]
	v_pk_mul_f32 v[8:9], v[144:145], v[12:13] op_sel_hi:[1,0]
	v_pk_mul_f32 v[10:11], v[146:147], v[12:13] op_sel_hi:[1,0]
	v_pk_mul_f32 v[12:13], v[150:151], v[12:13] op_sel_hi:[1,0]
	v_pk_fma_f32 v[8:9], v[18:19], v[8:9], v[2:3]
	v_pk_fma_f32 v[10:11], v[20:21], v[10:11], v[0:1]
	v_pk_fma_f32 v[22:23], v[14:15], v[22:23], v[6:7]
	v_pk_fma_f32 v[12:13], v[16:17], v[12:13], v[4:5]
	v_cvt_pk_bf16_f32 v136, v10, v11
	v_cvt_pk_bf16_f32 v137, v8, v9
	v_lshlrev_b64 v[10:11], 11, v[180:181]
	v_cvt_pk_bf16_f32 v138, v12, v13
	v_cvt_pk_bf16_f32 v139, v22, v23
	ds_read_b32 v8, v208
	v_lshl_add_u64 v[10:11], s[46:47], 0, v[10:11]
	v_lshl_add_u64 v[10:11], v[10:11], 0, v[112:113]
	global_store_dwordx4 v[10:11], v[136:139], off
	s_waitcnt lgkmcnt(0)
	v_pk_mul_f32 v[12:13], v[94:95], v[8:9] op_sel_hi:[1,0]
	v_pk_mul_f32 v[22:23], v[92:93], v[8:9] op_sel_hi:[1,0]
	v_pk_mul_f32 v[90:91], v[90:91], v[8:9] op_sel_hi:[1,0]
	v_pk_mul_f32 v[8:9], v[88:89], v[8:9] op_sel_hi:[1,0]
	v_pk_fma_f32 v[12:13], v[18:19], v[12:13], v[2:3]
	v_pk_fma_f32 v[22:23], v[20:21], v[22:23], v[0:1]
	v_pk_fma_f32 v[92:93], v[14:15], v[90:91], v[6:7]
	v_pk_fma_f32 v[8:9], v[16:17], v[8:9], v[4:5]
	v_cvt_pk_bf16_f32 v88, v22, v23
	v_cvt_pk_bf16_f32 v89, v12, v13
	s_nop 0
	v_cvt_pk_bf16_f32 v90, v8, v9
	v_cvt_pk_bf16_f32 v91, v92, v93
	ds_read_b32 v12, v209
	v_lshlrev_b64 v[8:9], 11, v[184:185]
	v_lshl_add_u64 v[8:9], s[46:47], 0, v[8:9]
	v_lshl_add_u64 v[8:9], v[8:9], 0, v[112:113]
	global_store_dwordx4 v[8:9], v[88:91], off
	s_waitcnt lgkmcnt(0)
	v_pk_mul_f32 v[22:23], v[100:101], v[12:13] op_sel_hi:[1,0]
	v_pk_mul_f32 v[88:89], v[102:103], v[12:13] op_sel_hi:[1,0]
	v_pk_mul_f32 v[90:91], v[174:175], v[12:13] op_sel_hi:[1,0]
	v_pk_mul_f32 v[12:13], v[176:177], v[12:13] op_sel_hi:[1,0]
	v_pk_fma_f32 v[22:23], v[18:19], v[22:23], v[2:3]
	v_pk_fma_f32 v[88:89], v[20:21], v[88:89], v[0:1]
	v_pk_fma_f32 v[92:93], v[14:15], v[90:91], v[6:7]
	v_pk_fma_f32 v[12:13], v[16:17], v[12:13], v[4:5]
	v_cvt_pk_bf16_f32 v88, v88, v89
	v_cvt_pk_bf16_f32 v89, v22, v23
	s_nop 0
	v_cvt_pk_bf16_f32 v90, v12, v13
	v_cvt_pk_bf16_f32 v91, v92, v93
	ds_read_b32 v22, v210
	v_lshlrev_b64 v[12:13], 11, v[178:179]
	v_lshl_add_u64 v[12:13], s[46:47], 0, v[12:13]
	v_lshl_add_u64 v[12:13], v[12:13], 0, v[112:113]
	global_store_dwordx4 v[12:13], v[88:91], off
	s_waitcnt lgkmcnt(0)
	v_pk_mul_f32 v[62:63], v[62:63], v[22:23] op_sel_hi:[1,0]
	v_pk_mul_f32 v[60:61], v[60:61], v[22:23] op_sel_hi:[1,0]
	v_pk_mul_f32 v[58:59], v[58:59], v[22:23] op_sel_hi:[1,0]
	v_pk_mul_f32 v[22:23], v[56:57], v[22:23] op_sel_hi:[1,0]
	v_pk_fma_f32 v[60:61], v[20:21], v[60:61], v[0:1]
	v_pk_fma_f32 v[22:23], v[16:17], v[22:23], v[4:5]
	v_pk_fma_f32 v[62:63], v[18:19], v[62:63], v[2:3]
	v_pk_fma_f32 v[88:89], v[14:15], v[58:59], v[6:7]
	v_cvt_pk_bf16_f32 v56, v60, v61
	v_cvt_pk_bf16_f32 v57, v62, v63
	v_cvt_pk_bf16_f32 v58, v22, v23
	v_add_u32_e32 v22, s35, v201
	v_cvt_pk_bf16_f32 v59, v88, v89
	ds_read_b32 v60, v211
	v_ashrrev_i32_e32 v23, 31, v22
	v_lshlrev_b64 v[22:23], 11, v[22:23]
	v_lshl_add_u64 v[22:23], s[46:47], 0, v[22:23]
	v_lshl_add_u64 v[22:23], v[22:23], 0, v[112:113]
	global_store_dwordx4 v[22:23], v[56:59], off
	s_waitcnt lgkmcnt(0)
	v_pk_mul_f32 v[62:63], v[68:69], v[60:61] op_sel_hi:[1,0]
	v_pk_mul_f32 v[56:57], v[64:65], v[60:61] op_sel_hi:[1,0]
	v_pk_mul_f32 v[58:59], v[66:67], v[60:61] op_sel_hi:[1,0]
	v_pk_mul_f32 v[60:61], v[70:71], v[60:61] op_sel_hi:[1,0]
	v_pk_fma_f32 v[56:57], v[18:19], v[56:57], v[2:3]
	v_pk_fma_f32 v[58:59], v[20:21], v[58:59], v[0:1]
	v_pk_fma_f32 v[62:63], v[14:15], v[62:63], v[6:7]
	v_pk_fma_f32 v[60:61], v[16:17], v[60:61], v[4:5]
	v_cvt_pk_bf16_f32 v58, v58, v59
	v_cvt_pk_bf16_f32 v59, v56, v57
	v_add_u32_e32 v56, s35, v202
	v_cvt_pk_bf16_f32 v60, v60, v61
	v_cvt_pk_bf16_f32 v61, v62, v63
	ds_read_b32 v62, v212
	v_ashrrev_i32_e32 v57, 31, v56
	v_lshlrev_b64 v[56:57], 11, v[56:57]
	v_lshl_add_u64 v[56:57], s[46:47], 0, v[56:57]
	v_lshl_add_u64 v[56:57], v[56:57], 0, v[112:113]
	global_store_dwordx4 v[56:57], v[58:61], off
	s_waitcnt lgkmcnt(0)
	v_pk_mul_f32 v[64:65], v[170:171], v[62:63] op_sel_hi:[1,0]
	v_pk_mul_f32 v[58:59], v[96:97], v[62:63] op_sel_hi:[1,0]
	v_pk_mul_f32 v[60:61], v[98:99], v[62:63] op_sel_hi:[1,0]
	v_pk_mul_f32 v[62:63], v[172:173], v[62:63] op_sel_hi:[1,0]
	v_pk_fma_f32 v[58:59], v[18:19], v[58:59], v[2:3]
	v_pk_fma_f32 v[60:61], v[20:21], v[60:61], v[0:1]
	v_pk_fma_f32 v[64:65], v[14:15], v[64:65], v[6:7]
	v_pk_fma_f32 v[62:63], v[16:17], v[62:63], v[4:5]
	v_cvt_pk_bf16_f32 v60, v60, v61
	v_cvt_pk_bf16_f32 v61, v58, v59
	v_add_u32_e32 v58, s35, v203
	v_cvt_pk_bf16_f32 v62, v62, v63
	v_cvt_pk_bf16_f32 v63, v64, v65
	ds_read_b32 v64, v213
	v_ashrrev_i32_e32 v59, 31, v58
	v_lshlrev_b64 v[58:59], 11, v[58:59]
	v_lshl_add_u64 v[58:59], s[46:47], 0, v[58:59]
	v_lshl_add_u64 v[58:59], v[58:59], 0, v[112:113]
	global_store_dwordx4 v[58:59], v[60:63], off
	s_waitcnt lgkmcnt(0)
	s_nop 0
	v_pk_mul_f32 v[62:63], v[132:133], v[64:65] op_sel_hi:[1,0]
	v_pk_mul_f32 v[60:61], v[134:135], v[64:65] op_sel_hi:[1,0]
	v_pk_fma_f32 v[0:1], v[20:21], v[62:63], v[0:1]
	v_pk_mul_f32 v[20:21], v[128:129], v[64:65] op_sel_hi:[1,0]
	v_pk_fma_f32 v[2:3], v[18:19], v[60:61], v[2:3]
	v_pk_fma_f32 v[4:5], v[16:17], v[20:21], v[4:5]
	v_cvt_pk_bf16_f32 v0, v0, v1
	v_cvt_pk_bf16_f32 v1, v2, v3
	v_pk_mul_f32 v[18:19], v[130:131], v[64:65] op_sel_hi:[1,0]
	v_cvt_pk_bf16_f32 v2, v4, v5
	v_add_u32_e32 v4, s35, v204
	v_ashrrev_i32_e32 v5, 31, v4
	v_lshlrev_b64 v[4:5], 11, v[4:5]
	v_lshl_add_u64 v[4:5], s[46:47], 0, v[4:5]
	v_pk_fma_f32 v[6:7], v[14:15], v[18:19], v[6:7]
	v_lshl_add_u64 v[14:15], v[4:5], 0, v[112:113]
	v_cvt_pk_bf16_f32 v3, v6, v7
	global_store_dwordx4 v[14:15], v[0:3], off
	s_nop 1
	v_mov_b32_e32 v16, v228
	v_mov_b32_e32 v17, v229
	v_mov_b32_e32 v18, v230
	v_mov_b32_e32 v19, v231
	v_mov_b32_e32 v60, v232
	v_mov_b32_e32 v61, v233
	v_mov_b32_e32 v62, v234
	v_mov_b32_e32 v63, v235
	v_mov_b32_e32 v64, v236
	v_mov_b32_e32 v65, v237
	v_mov_b32_e32 v66, v238
	v_mov_b32_e32 v67, v239
	v_mov_b32_e32 v68, v240
	v_mov_b32_e32 v69, v241
	v_mov_b32_e32 v70, v242
	v_mov_b32_e32 v71, v243
	v_mov_b32_e32 v4, v248
	v_mov_b32_e32 v5, v249
	v_mov_b32_e32 v6, v250
	v_mov_b32_e32 v7, v251
	v_mov_b32_e32 v0, v252
	v_mov_b32_e32 v1, v253
	v_mov_b32_e32 v2, v254
	v_mov_b32_e32 v3, v255
	ds_read_b32 v20, v206
	s_waitcnt lgkmcnt(0)
	v_pk_mul_f32 v[88:89], v[126:127], v[20:21] op_sel_hi:[1,0]
	v_pk_mul_f32 v[90:91], v[124:125], v[20:21] op_sel_hi:[1,0]
	v_pk_mul_f32 v[92:93], v[118:119], v[20:21] op_sel_hi:[1,0]
	v_pk_mul_f32 v[94:95], v[116:117], v[20:21] op_sel_hi:[1,0]
	s_nop 0
	v_pk_add_f32 v[18:19], v[18:19], 1.0 op_sel_hi:[1,0]
	v_pk_add_f32 v[16:17], v[16:17], 1.0 op_sel_hi:[1,0]
	v_pk_add_f32 v[62:63], v[62:63], 1.0 op_sel_hi:[1,0]
	v_pk_add_f32 v[96:97], v[60:61], 1.0 op_sel_hi:[1,0]
	v_pk_mul_f32 v[20:21], v[66:67], v[18:19]
	v_pk_mul_f32 v[60:61], v[64:65], v[16:17]
	v_pk_mul_f32 v[16:17], v[70:71], v[62:63]
	v_pk_mul_f32 v[18:19], v[68:69], v[96:97]
	v_pk_fma_f32 v[64:65], v[20:21], v[88:89], v[6:7]
	v_pk_fma_f32 v[62:63], v[60:61], v[90:91], v[4:5]
	v_pk_fma_f32 v[66:67], v[16:17], v[92:93], v[2:3]
	v_pk_fma_f32 v[68:69], v[18:19], v[94:95], v[0:1]
	v_cvt_pk_bf16_f32 v62, v62, v63
	v_cvt_pk_bf16_f32 v63, v64, v65
	s_nop 0
	v_cvt_pk_bf16_f32 v64, v68, v69
	v_cvt_pk_bf16_f32 v65, v66, v67
	ds_read_b32 v66, v207
	global_store_dwordx4 v[168:169], v[62:65], off offset:256
	s_waitcnt lgkmcnt(0)
	v_pk_mul_f32 v[68:69], v[108:109], v[66:67] op_sel_hi:[1,0]
	v_pk_mul_f32 v[62:63], v[104:105], v[66:67] op_sel_hi:[1,0]
	v_pk_mul_f32 v[64:65], v[106:107], v[66:67] op_sel_hi:[1,0]
	v_pk_mul_f32 v[66:67], v[110:111], v[66:67] op_sel_hi:[1,0]
	v_pk_fma_f32 v[70:71], v[20:21], v[62:63], v[6:7]
	v_pk_fma_f32 v[62:63], v[60:61], v[64:65], v[4:5]
	v_pk_fma_f32 v[64:65], v[18:19], v[66:67], v[0:1]
	v_pk_fma_f32 v[68:69], v[16:17], v[68:69], v[2:3]
	v_cvt_pk_bf16_f32 v62, v62, v63
	v_cvt_pk_bf16_f32 v63, v70, v71
	v_cvt_pk_bf16_f32 v64, v64, v65
	s_nop 0
	v_cvt_pk_bf16_f32 v65, v68, v69
	ds_read_b32 v66, v208
	global_store_dwordx4 v[10:11], v[62:65], off offset:256
	s_waitcnt lgkmcnt(0)
	v_pk_mul_f32 v[10:11], v[86:87], v[66:67] op_sel_hi:[1,0]
	v_pk_mul_f32 v[62:63], v[84:85], v[66:67] op_sel_hi:[1,0]
	v_pk_mul_f32 v[64:65], v[82:83], v[66:67] op_sel_hi:[1,0]
	v_pk_mul_f32 v[66:67], v[80:81], v[66:67] op_sel_hi:[1,0]
	v_pk_fma_f32 v[10:11], v[20:21], v[10:11], v[6:7]
	v_pk_fma_f32 v[62:63], v[60:61], v[62:63], v[4:5]
	v_pk_fma_f32 v[68:69], v[16:17], v[64:65], v[2:3]
	v_pk_fma_f32 v[64:65], v[18:19], v[66:67], v[0:1]
	v_cvt_pk_bf16_f32 v62, v62, v63
	v_cvt_pk_bf16_f32 v63, v10, v11
	s_nop 0
	v_cvt_pk_bf16_f32 v64, v64, v65
	v_cvt_pk_bf16_f32 v65, v68, v69
	ds_read_b32 v10, v209
	global_store_dwordx4 v[8:9], v[62:65], off offset:256
	s_waitcnt lgkmcnt(0)
	v_pk_mul_f32 v[8:9], v[72:73], v[10:11] op_sel_hi:[1,0]
	v_pk_mul_f32 v[62:63], v[74:75], v[10:11] op_sel_hi:[1,0]
	v_pk_fma_f32 v[64:65], v[20:21], v[8:9], v[6:7]
	v_pk_fma_f32 v[8:9], v[60:61], v[62:63], v[4:5]
	v_pk_mul_f32 v[62:63], v[76:77], v[10:11] op_sel_hi:[1,0]
	v_pk_mul_f32 v[10:11], v[78:79], v[10:11] op_sel_hi:[1,0]
	v_pk_fma_f32 v[62:63], v[16:17], v[62:63], v[2:3]
	v_pk_fma_f32 v[10:11], v[18:19], v[10:11], v[0:1]
	v_cvt_pk_bf16_f32 v8, v8, v9
	v_cvt_pk_bf16_f32 v9, v64, v65
	s_nop 0
	v_cvt_pk_bf16_f32 v10, v10, v11
	v_cvt_pk_bf16_f32 v11, v62, v63
	ds_read_b32 v62, v210
	global_store_dwordx4 v[12:13], v[8:11], off offset:256
	s_waitcnt lgkmcnt(0)
	v_pk_mul_f32 v[48:49], v[48:49], v[62:63] op_sel_hi:[1,0]
	v_pk_mul_f32 v[8:9], v[54:55], v[62:63] op_sel_hi:[1,0]
	v_pk_mul_f32 v[10:11], v[52:53], v[62:63] op_sel_hi:[1,0]
	v_pk_fma_f32 v[12:13], v[20:21], v[8:9], v[6:7]
	v_pk_fma_f32 v[8:9], v[60:61], v[10:11], v[4:5]
	v_pk_mul_f32 v[10:11], v[50:51], v[62:63] op_sel_hi:[1,0]
	v_cvt_pk_bf16_f32 v8, v8, v9
	v_cvt_pk_bf16_f32 v9, v12, v13
	s_nop 0
	v_pk_fma_f32 v[50:51], v[16:17], v[10:11], v[2:3]
	v_pk_fma_f32 v[10:11], v[18:19], v[48:49], v[0:1]
	s_nop 0
	v_cvt_pk_bf16_f32 v10, v10, v11
	v_cvt_pk_bf16_f32 v11, v50, v51
	ds_read_b32 v12, v211
	global_store_dwordx4 v[22:23], v[8:11], off offset:256
	s_waitcnt lgkmcnt(0)
	s_nop 0
	v_pk_mul_f32 v[8:9], v[40:41], v[12:13] op_sel_hi:[1,0]
	v_pk_mul_f32 v[10:11], v[42:43], v[12:13] op_sel_hi:[1,0]
	v_pk_fma_f32 v[22:23], v[20:21], v[8:9], v[6:7]
	v_pk_fma_f32 v[8:9], v[60:61], v[10:11], v[4:5]
	v_pk_mul_f32 v[10:11], v[44:45], v[12:13] op_sel_hi:[1,0]
	v_pk_mul_f32 v[12:13], v[46:47], v[12:13] op_sel_hi:[1,0]
	v_pk_fma_f32 v[40:41], v[16:17], v[10:11], v[2:3]
	v_pk_fma_f32 v[10:11], v[18:19], v[12:13], v[0:1]
	v_cvt_pk_bf16_f32 v8, v8, v9
	v_cvt_pk_bf16_f32 v9, v22, v23
	s_nop 0
	v_cvt_pk_bf16_f32 v10, v10, v11
	v_cvt_pk_bf16_f32 v11, v40, v41
	ds_read_b32 v12, v212
	global_store_dwordx4 v[56:57], v[8:11], off offset:256
	s_waitcnt lgkmcnt(0)
	s_nop 0
	v_pk_mul_f32 v[8:9], v[24:25], v[12:13] op_sel_hi:[1,0]
	v_pk_mul_f32 v[10:11], v[26:27], v[12:13] op_sel_hi:[1,0]
	v_pk_fma_f32 v[22:23], v[20:21], v[8:9], v[6:7]
	v_pk_fma_f32 v[8:9], v[60:61], v[10:11], v[4:5]
	v_pk_mul_f32 v[10:11], v[28:29], v[12:13] op_sel_hi:[1,0]
	v_pk_mul_f32 v[12:13], v[30:31], v[12:13] op_sel_hi:[1,0]
	v_pk_fma_f32 v[24:25], v[16:17], v[10:11], v[2:3]
	v_pk_fma_f32 v[10:11], v[18:19], v[12:13], v[0:1]
	v_cvt_pk_bf16_f32 v8, v8, v9
	v_cvt_pk_bf16_f32 v9, v22, v23
	s_nop 0
	v_cvt_pk_bf16_f32 v10, v10, v11
	v_cvt_pk_bf16_f32 v11, v24, v25
	ds_read_b32 v12, v213
	global_store_dwordx4 v[58:59], v[8:11], off offset:256
	s_waitcnt lgkmcnt(0)
	s_nop 0
	v_pk_mul_f32 v[8:9], v[32:33], v[12:13] op_sel_hi:[1,0]
	v_pk_mul_f32 v[10:11], v[34:35], v[12:13] op_sel_hi:[1,0]
	v_pk_fma_f32 v[6:7], v[20:21], v[8:9], v[6:7]
	v_pk_fma_f32 v[4:5], v[60:61], v[10:11], v[4:5]
	v_pk_mul_f32 v[8:9], v[36:37], v[12:13] op_sel_hi:[1,0]
	v_pk_mul_f32 v[10:11], v[38:39], v[12:13] op_sel_hi:[1,0]
	v_pk_fma_f32 v[8:9], v[16:17], v[8:9], v[2:3]
	v_pk_fma_f32 v[2:3], v[18:19], v[10:11], v[0:1]
	v_cvt_pk_bf16_f32 v0, v4, v5
	v_cvt_pk_bf16_f32 v1, v6, v7
	s_nop 0
	v_cvt_pk_bf16_f32 v2, v2, v3
	v_cvt_pk_bf16_f32 v3, v8, v9
	global_store_dwordx4 v[14:15], v[0:3], off offset:256
	s_cbranch_vccnz .LBB0_338
	s_andn2_b64 vcc, exec, s[16:17]
	s_cbranch_vccnz .LBB0_337
	s_barrier
	s_branch .LBB0_337

.LBB0_537:
	s_or_b64 exec, exec, s[78:79]
	s_add_u32 s0, s91, s80
	s_addc_u32 s1, s94, s81
	v_lshlrev_b64 v[66:67], 2, v[170:171]
	v_lshl_add_u64 v[68:69], s[66:67], 0, v[66:67]
	v_lshl_add_u64 v[66:67], s[0:1], 0, v[66:67]
	s_mov_b64 s[0:1], 0x1000
	v_lshl_add_u64 v[70:71], v[66:67], 0, s[0:1]
	s_movk_i32 s0, 0x1000
	v_add_co_u32_e32 v112, vcc, s0, v66
	s_waitcnt vmcnt(0) lgkmcnt(0)
	s_barrier
	s_nop 0
	v_addc_co_u32_e32 v113, vcc, 0, v67, vcc
	flat_load_dwordx4 v[0:3], v[68:69]
	flat_load_dwordx4 v[4:7], v[68:69] offset:16
	s_nop 0
	global_load_dwordx4 v[112:115], v[112:113], off
	s_nop 0
	global_load_dwordx4 v[130:133], v[70:71], off offset:16
	s_mov_b64 s[0:1], -1
	s_andn2_b64 vcc, exec, s[10:11]
	s_waitcnt vmcnt(0)
	v_pk_add_f32 v[114:115], v[114:115], 1.0 op_sel_hi:[1,0]
	v_pk_add_f32 v[112:113], v[112:113], 1.0 op_sel_hi:[1,0]
	s_waitcnt lgkmcnt(0)
	v_pk_mul_f32 v[122:123], v[2:3], v[114:115]
	v_pk_mul_f32 v[128:129], v[0:1], v[112:113]
	v_pk_add_f32 v[0:1], v[132:133], 1.0 op_sel_hi:[1,0]
	v_pk_add_f32 v[2:3], v[130:131], 1.0 op_sel_hi:[1,0]
	v_pk_mul_f32 v[114:115], v[6:7], v[0:1]
	v_pk_mul_f32 v[120:121], v[4:5], v[2:3]
	global_load_dwordx4 v[0:3], v[66:67], off offset:16
	global_load_dwordx4 v[4:7], v[66:67], off
	global_load_dwordx4 v[228:231], v[68:69], off offset:512
	global_load_dwordx4 v[232:235], v[68:69], off offset:528
	global_load_dwordx4 v[236:239], v[70:71], off offset:528
	global_load_dwordx4 v[240:243], v[70:71], off offset:512
	global_load_dwordx4 v[248:251], v[66:67], off offset:528
	global_load_dwordx4 v[252:255], v[66:67], off offset:512
	ds_read_b32 v112, v206
	s_waitcnt lgkmcnt(0)
	v_pk_mul_f32 v[130:131], v[142:143], v[112:113] op_sel_hi:[1,0]
	v_pk_mul_f32 v[132:133], v[140:141], v[112:113] op_sel_hi:[1,0]
	s_waitcnt vmcnt(0)
	v_pk_fma_f32 v[134:135], v[122:123], v[130:131], v[6:7]
	v_pk_fma_f32 v[130:131], v[128:129], v[132:133], v[4:5]
	v_pk_mul_f32 v[132:133], v[138:139], v[112:113] op_sel_hi:[1,0]
	v_pk_mul_f32 v[112:113], v[136:137], v[112:113] op_sel_hi:[1,0]
	v_pk_fma_f32 v[136:137], v[114:115], v[132:133], v[2:3]
	v_pk_fma_f32 v[112:113], v[120:121], v[112:113], v[0:1]
	v_cvt_pk_bf16_f32 v130, v130, v131
	v_cvt_pk_bf16_f32 v131, v134, v135
	s_nop 0
	v_cvt_pk_bf16_f32 v132, v112, v113
	v_lshl_add_u64 v[112:113], s[46:47], 0, v[168:169]
	v_lshl_add_u64 v[112:113], v[112:113], 0, v[64:65]
	v_cvt_pk_bf16_f32 v133, v136, v137
	global_store_dwordx4 v[112:113], v[130:133], off
	ds_read_b32 v130, v207
	s_waitcnt lgkmcnt(0)
	v_pk_mul_f32 v[134:135], v[146:147], v[130:131] op_sel_hi:[1,0]
	v_pk_mul_f32 v[132:133], v[144:145], v[130:131] op_sel_hi:[1,0]
	s_nop 0
	v_pk_fma_f32 v[136:137], v[122:123], v[132:133], v[6:7]
	v_pk_fma_f32 v[132:133], v[128:129], v[134:135], v[4:5]
	v_pk_mul_f32 v[134:135], v[148:149], v[130:131] op_sel_hi:[1,0]
	v_pk_mul_f32 v[130:131], v[150:151], v[130:131] op_sel_hi:[1,0]
	v_pk_fma_f32 v[138:139], v[114:115], v[134:135], v[2:3]
	v_pk_fma_f32 v[130:131], v[120:121], v[130:131], v[0:1]
	v_cvt_pk_bf16_f32 v132, v132, v133
	v_cvt_pk_bf16_f32 v133, v136, v137
	s_nop 0
	v_cvt_pk_bf16_f32 v134, v130, v131
	v_add_u32_e32 v130, s71, v198
	v_ashrrev_i32_e32 v131, 31, v130
	v_lshlrev_b64 v[130:131], 11, v[130:131]
	v_lshl_add_u64 v[130:131], s[46:47], 0, v[130:131]
	v_lshl_add_u64 v[130:131], v[130:131], 0, v[64:65]
	v_cvt_pk_bf16_f32 v135, v138, v139
	global_store_dwordx4 v[130:131], v[132:135], off
	ds_read_b32 v132, v208
	s_waitcnt lgkmcnt(0)
	v_pk_mul_f32 v[136:137], v[174:175], v[132:133] op_sel_hi:[1,0]
	v_pk_mul_f32 v[134:135], v[172:173], v[132:133] op_sel_hi:[1,0]
	s_nop 0
	v_pk_fma_f32 v[138:139], v[122:123], v[134:135], v[6:7]
	v_pk_fma_f32 v[134:135], v[128:129], v[136:137], v[4:5]
	v_pk_mul_f32 v[136:137], v[176:177], v[132:133] op_sel_hi:[1,0]
	v_pk_mul_f32 v[132:133], v[178:179], v[132:133] op_sel_hi:[1,0]
	v_pk_fma_f32 v[140:141], v[114:115], v[136:137], v[2:3]
	v_pk_fma_f32 v[132:133], v[120:121], v[132:133], v[0:1]
	v_cvt_pk_bf16_f32 v134, v134, v135
	v_cvt_pk_bf16_f32 v135, v138, v139
	s_nop 0
	v_cvt_pk_bf16_f32 v136, v132, v133
	v_add_u32_e32 v132, s71, v199
	v_ashrrev_i32_e32 v133, 31, v132
	v_lshlrev_b64 v[132:133], 11, v[132:133]
	v_lshl_add_u64 v[132:133], s[46:47], 0, v[132:133]
	v_lshl_add_u64 v[132:133], v[132:133], 0, v[64:65]
	v_cvt_pk_bf16_f32 v137, v140, v141
	global_store_dwordx4 v[132:133], v[134:137], off
	ds_read_b32 v134, v209
	s_waitcnt lgkmcnt(0)
	v_pk_mul_f32 v[96:97], v[96:97], v[134:135] op_sel_hi:[1,0]
	v_pk_mul_f32 v[98:99], v[98:99], v[134:135] op_sel_hi:[1,0]
	v_pk_fma_f32 v[96:97], v[122:123], v[96:97], v[6:7]
	v_pk_fma_f32 v[98:99], v[128:129], v[98:99], v[4:5]
	v_pk_mul_f32 v[100:101], v[100:101], v[134:135] op_sel_hi:[1,0]
	v_cvt_pk_bf16_f32 v98, v98, v99
	v_cvt_pk_bf16_f32 v99, v96, v97
	v_add_u32_e32 v96, s71, v200
	v_ashrrev_i32_e32 v97, 31, v96
	v_lshlrev_b64 v[96:97], 11, v[96:97]
	v_pk_mul_f32 v[102:103], v[102:103], v[134:135] op_sel_hi:[1,0]
	v_lshl_add_u64 v[96:97], s[46:47], 0, v[96:97]
	v_pk_fma_f32 v[134:135], v[114:115], v[100:101], v[2:3]
	v_pk_fma_f32 v[100:101], v[120:121], v[102:103], v[0:1]
	v_lshl_add_u64 v[96:97], v[96:97], 0, v[64:65]
	v_cvt_pk_bf16_f32 v100, v100, v101
	v_cvt_pk_bf16_f32 v101, v134, v135
	global_store_dwordx4 v[96:97], v[98:101], off
	ds_read_b32 v98, v210
	s_waitcnt lgkmcnt(0)
	v_pk_mul_f32 v[88:89], v[88:89], v[98:99] op_sel_hi:[1,0]
	v_pk_mul_f32 v[90:91], v[90:91], v[98:99] op_sel_hi:[1,0]
	v_pk_fma_f32 v[88:89], v[122:123], v[88:89], v[6:7]
	v_pk_fma_f32 v[90:91], v[128:129], v[90:91], v[4:5]
	v_pk_mul_f32 v[92:93], v[92:93], v[98:99] op_sel_hi:[1,0]
	v_cvt_pk_bf16_f32 v90, v90, v91
	v_cvt_pk_bf16_f32 v91, v88, v89
	v_add_u32_e32 v88, s71, v201
	v_ashrrev_i32_e32 v89, 31, v88
	v_lshlrev_b64 v[88:89], 11, v[88:89]
	v_pk_mul_f32 v[94:95], v[94:95], v[98:99] op_sel_hi:[1,0]
	v_lshl_add_u64 v[88:89], s[46:47], 0, v[88:89]
	v_pk_fma_f32 v[98:99], v[114:115], v[92:93], v[2:3]
	v_pk_fma_f32 v[92:93], v[120:121], v[94:95], v[0:1]
	v_lshl_add_u64 v[88:89], v[88:89], 0, v[64:65]
	v_cvt_pk_bf16_f32 v92, v92, v93
	v_cvt_pk_bf16_f32 v93, v98, v99
	global_store_dwordx4 v[88:89], v[90:93], off
	ds_read_b32 v90, v211
	s_waitcnt lgkmcnt(0)
	v_pk_mul_f32 v[56:57], v[56:57], v[90:91] op_sel_hi:[1,0]
	v_pk_mul_f32 v[58:59], v[58:59], v[90:91] op_sel_hi:[1,0]
	v_pk_fma_f32 v[56:57], v[122:123], v[56:57], v[6:7]
	v_pk_fma_f32 v[58:59], v[128:129], v[58:59], v[4:5]
	v_pk_mul_f32 v[60:61], v[60:61], v[90:91] op_sel_hi:[1,0]
	v_cvt_pk_bf16_f32 v58, v58, v59
	v_cvt_pk_bf16_f32 v59, v56, v57
	v_add_u32_e32 v56, s71, v202
	v_ashrrev_i32_e32 v57, 31, v56
	v_lshlrev_b64 v[56:57], 11, v[56:57]
	v_pk_mul_f32 v[62:63], v[62:63], v[90:91] op_sel_hi:[1,0]
	v_lshl_add_u64 v[56:57], s[46:47], 0, v[56:57]
	v_pk_fma_f32 v[90:91], v[114:115], v[60:61], v[2:3]
	v_pk_fma_f32 v[60:61], v[120:121], v[62:63], v[0:1]
	v_lshl_add_u64 v[56:57], v[56:57], 0, v[64:65]
	v_cvt_pk_bf16_f32 v60, v60, v61
	v_cvt_pk_bf16_f32 v61, v90, v91
	global_store_dwordx4 v[56:57], v[58:61], off
	ds_read_b32 v58, v212
	s_waitcnt lgkmcnt(0)
	v_pk_mul_f32 v[28:29], v[28:29], v[58:59] op_sel_hi:[1,0]
	v_pk_mul_f32 v[24:25], v[24:25], v[58:59] op_sel_hi:[1,0]
	v_pk_mul_f32 v[30:31], v[30:31], v[58:59] op_sel_hi:[1,0]
	v_pk_fma_f32 v[28:29], v[128:129], v[28:29], v[4:5]
	v_pk_mul_f32 v[26:27], v[26:27], v[58:59] op_sel_hi:[1,0]
	v_pk_fma_f32 v[24:25], v[120:121], v[24:25], v[0:1]
	v_pk_fma_f32 v[30:31], v[122:123], v[30:31], v[6:7]
	v_pk_fma_f32 v[58:59], v[114:115], v[26:27], v[2:3]
	v_cvt_pk_bf16_f32 v26, v28, v29
	v_cvt_pk_bf16_f32 v27, v30, v31
	v_cvt_pk_bf16_f32 v28, v24, v25
	v_add_u32_e32 v24, s71, v203
	v_ashrrev_i32_e32 v25, 31, v24
	v_lshlrev_b64 v[24:25], 11, v[24:25]
	v_lshl_add_u64 v[24:25], s[46:47], 0, v[24:25]
	v_lshl_add_u64 v[24:25], v[24:25], 0, v[64:65]
	v_cvt_pk_bf16_f32 v29, v58, v59
	global_store_dwordx4 v[24:25], v[26:29], off
	ds_read_b32 v26, v213
	s_waitcnt lgkmcnt(0)
	v_pk_mul_f32 v[30:31], v[34:35], v[26:27] op_sel_hi:[1,0]
	v_pk_mul_f32 v[28:29], v[32:33], v[26:27] op_sel_hi:[1,0]
	v_pk_fma_f32 v[4:5], v[128:129], v[30:31], v[4:5]
	v_pk_fma_f32 v[6:7], v[122:123], v[28:29], v[6:7]
	v_pk_mul_f32 v[28:29], v[36:37], v[26:27] op_sel_hi:[1,0]
	v_pk_mul_f32 v[26:27], v[38:39], v[26:27] op_sel_hi:[1,0]
	v_pk_fma_f32 v[28:29], v[114:115], v[28:29], v[2:3]
	v_pk_fma_f32 v[2:3], v[120:121], v[26:27], v[0:1]
	v_cvt_pk_bf16_f32 v0, v4, v5
	v_add_u32_e32 v4, s71, v204
	v_ashrrev_i32_e32 v5, 31, v4
	v_lshlrev_b64 v[4:5], 11, v[4:5]
	v_lshl_add_u64 v[4:5], s[46:47], 0, v[4:5]
	v_lshl_add_u64 v[26:27], v[4:5], 0, v[64:65]
	v_cvt_pk_bf16_f32 v1, v6, v7
	v_cvt_pk_bf16_f32 v2, v2, v3
	v_cvt_pk_bf16_f32 v3, v28, v29
	global_store_dwordx4 v[26:27], v[0:3], off
	s_nop 1
	v_mov_b32_e32 v0, v228
	v_mov_b32_e32 v1, v229
	v_mov_b32_e32 v2, v230
	v_mov_b32_e32 v3, v231
	s_nop 0
	v_mov_b32_e32 v4, v232
	v_mov_b32_e32 v5, v233
	v_mov_b32_e32 v6, v234
	v_mov_b32_e32 v7, v235
	v_mov_b32_e32 v28, v236
	v_mov_b32_e32 v29, v237
	v_mov_b32_e32 v30, v238
	v_mov_b32_e32 v31, v239
	v_mov_b32_e32 v32, v240
	v_mov_b32_e32 v33, v241
	v_mov_b32_e32 v34, v242
	v_mov_b32_e32 v35, v243
	s_nop 0
	v_pk_add_f32 v[34:35], v[34:35], 1.0 op_sel_hi:[1,0]
	v_pk_add_f32 v[36:37], v[32:33], 1.0 op_sel_hi:[1,0]
	s_waitcnt lgkmcnt(0)
	v_pk_mul_f32 v[32:33], v[2:3], v[34:35]
	v_pk_mul_f32 v[34:35], v[0:1], v[36:37]
	v_pk_add_f32 v[0:1], v[30:31], 1.0 op_sel_hi:[1,0]
	v_pk_add_f32 v[2:3], v[28:29], 1.0 op_sel_hi:[1,0]
	v_pk_mul_f32 v[28:29], v[6:7], v[0:1]
	v_pk_mul_f32 v[30:31], v[4:5], v[2:3]
	v_mov_b32_e32 v0, v248
	v_mov_b32_e32 v1, v249
	v_mov_b32_e32 v2, v250
	v_mov_b32_e32 v3, v251
	v_mov_b32_e32 v4, v252
	v_mov_b32_e32 v5, v253
	v_mov_b32_e32 v6, v254
	v_mov_b32_e32 v7, v255
	ds_read_b32 v36, v206
	s_waitcnt lgkmcnt(0)
	v_pk_mul_f32 v[38:39], v[126:127], v[36:37] op_sel_hi:[1,0]
	v_pk_mul_f32 v[58:59], v[124:125], v[36:37] op_sel_hi:[1,0]
	v_pk_mul_f32 v[60:61], v[118:119], v[36:37] op_sel_hi:[1,0]
	v_pk_mul_f32 v[36:37], v[116:117], v[36:37] op_sel_hi:[1,0]
	s_nop 0
	v_pk_fma_f32 v[60:61], v[28:29], v[60:61], v[2:3]
	s_nop 0
	v_pk_fma_f32 v[38:39], v[32:33], v[38:39], v[6:7]
	v_pk_fma_f32 v[58:59], v[34:35], v[58:59], v[4:5]
	v_pk_fma_f32 v[62:63], v[30:31], v[36:37], v[0:1]
	v_cvt_pk_bf16_f32 v36, v58, v59
	v_cvt_pk_bf16_f32 v37, v38, v39
	s_nop 0
	v_cvt_pk_bf16_f32 v38, v62, v63
	v_cvt_pk_bf16_f32 v39, v60, v61
	global_store_dwordx4 v[112:113], v[36:39], off offset:256
	ds_read_b32 v36, v207
	s_waitcnt lgkmcnt(0)
	v_pk_mul_f32 v[58:59], v[108:109], v[36:37] op_sel_hi:[1,0]
	v_pk_mul_f32 v[38:39], v[104:105], v[36:37] op_sel_hi:[1,0]
	v_pk_mul_f32 v[60:61], v[106:107], v[36:37] op_sel_hi:[1,0]
	v_pk_mul_f32 v[36:37], v[110:111], v[36:37] op_sel_hi:[1,0]
	v_pk_fma_f32 v[38:39], v[32:33], v[38:39], v[6:7]
	v_pk_fma_f32 v[58:59], v[34:35], v[58:59], v[4:5]
	v_pk_fma_f32 v[62:63], v[30:31], v[36:37], v[0:1]
	v_cvt_pk_bf16_f32 v36, v58, v59
	v_pk_fma_f32 v[60:61], v[28:29], v[60:61], v[2:3]
	v_cvt_pk_bf16_f32 v37, v38, v39
	v_cvt_pk_bf16_f32 v38, v62, v63
	s_nop 0
	v_cvt_pk_bf16_f32 v39, v60, v61
	global_store_dwordx4 v[130:131], v[36:39], off offset:256
	ds_read_b32 v36, v208
	s_waitcnt lgkmcnt(0)
	v_pk_mul_f32 v[58:59], v[84:85], v[36:37] op_sel_hi:[1,0]
	v_pk_mul_f32 v[38:39], v[86:87], v[36:37] op_sel_hi:[1,0]
	v_pk_mul_f32 v[60:61], v[82:83], v[36:37] op_sel_hi:[1,0]
	v_pk_mul_f32 v[36:37], v[80:81], v[36:37] op_sel_hi:[1,0]
	v_pk_fma_f32 v[38:39], v[32:33], v[38:39], v[6:7]
	v_pk_fma_f32 v[58:59], v[34:35], v[58:59], v[4:5]
	v_pk_fma_f32 v[62:63], v[30:31], v[36:37], v[0:1]
	v_cvt_pk_bf16_f32 v36, v58, v59
	v_pk_fma_f32 v[60:61], v[28:29], v[60:61], v[2:3]
	v_cvt_pk_bf16_f32 v37, v38, v39
	v_cvt_pk_bf16_f32 v38, v62, v63
	s_nop 0
	v_cvt_pk_bf16_f32 v39, v60, v61
	global_store_dwordx4 v[132:133], v[36:39], off offset:256
	ds_read_b32 v36, v209
	s_waitcnt lgkmcnt(0)
	v_pk_mul_f32 v[58:59], v[76:77], v[36:37] op_sel_hi:[1,0]
	v_pk_mul_f32 v[38:39], v[72:73], v[36:37] op_sel_hi:[1,0]
	v_pk_mul_f32 v[60:61], v[74:75], v[36:37] op_sel_hi:[1,0]
	v_pk_mul_f32 v[36:37], v[78:79], v[36:37] op_sel_hi:[1,0]
	v_pk_fma_f32 v[38:39], v[32:33], v[38:39], v[6:7]
	v_pk_fma_f32 v[58:59], v[34:35], v[58:59], v[4:5]
	v_pk_fma_f32 v[62:63], v[30:31], v[36:37], v[0:1]
	v_cvt_pk_bf16_f32 v36, v58, v59
	v_pk_fma_f32 v[60:61], v[28:29], v[60:61], v[2:3]
	v_cvt_pk_bf16_f32 v37, v38, v39
	v_cvt_pk_bf16_f32 v38, v62, v63
	s_nop 0
	v_cvt_pk_bf16_f32 v39, v60, v61
	global_store_dwordx4 v[96:97], v[36:39], off offset:256
	ds_read_b32 v36, v210
	s_waitcnt lgkmcnt(0)
	v_pk_mul_f32 v[52:53], v[52:53], v[36:37] op_sel_hi:[1,0]
	v_pk_mul_f32 v[38:39], v[54:55], v[36:37] op_sel_hi:[1,0]
	v_pk_mul_f32 v[50:51], v[50:51], v[36:37] op_sel_hi:[1,0]
	v_pk_mul_f32 v[36:37], v[48:49], v[36:37] op_sel_hi:[1,0]
	v_pk_fma_f32 v[38:39], v[32:33], v[38:39], v[6:7]
	v_pk_fma_f32 v[52:53], v[34:35], v[52:53], v[4:5]
	v_pk_fma_f32 v[48:49], v[28:29], v[50:51], v[2:3]
	v_pk_fma_f32 v[50:51], v[30:31], v[36:37], v[0:1]
	v_cvt_pk_bf16_f32 v36, v52, v53
	v_cvt_pk_bf16_f32 v37, v38, v39
	s_nop 0
	v_cvt_pk_bf16_f32 v38, v50, v51
	v_cvt_pk_bf16_f32 v39, v48, v49
	global_store_dwordx4 v[88:89], v[36:39], off offset:256
	ds_read_b32 v36, v211
	s_waitcnt lgkmcnt(0)
	v_pk_mul_f32 v[38:39], v[40:41], v[36:37] op_sel_hi:[1,0]
	v_pk_mul_f32 v[40:41], v[42:43], v[36:37] op_sel_hi:[1,0]
	v_pk_mul_f32 v[42:43], v[44:45], v[36:37] op_sel_hi:[1,0]
	v_pk_mul_f32 v[36:37], v[46:47], v[36:37] op_sel_hi:[1,0]
	v_pk_fma_f32 v[38:39], v[32:33], v[38:39], v[6:7]
	v_pk_fma_f32 v[40:41], v[34:35], v[40:41], v[4:5]
	v_pk_fma_f32 v[44:45], v[30:31], v[36:37], v[0:1]
	v_cvt_pk_bf16_f32 v36, v40, v41
	v_pk_fma_f32 v[42:43], v[28:29], v[42:43], v[2:3]
	v_cvt_pk_bf16_f32 v37, v38, v39
	v_cvt_pk_bf16_f32 v38, v44, v45
	s_nop 0
	v_cvt_pk_bf16_f32 v39, v42, v43
	global_store_dwordx4 v[56:57], v[36:39], off offset:256
	ds_read_b32 v36, v212
	s_waitcnt lgkmcnt(0)
	v_pk_mul_f32 v[20:21], v[20:21], v[36:37] op_sel_hi:[1,0]
	v_pk_mul_f32 v[18:19], v[18:19], v[36:37] op_sel_hi:[1,0]
	v_pk_mul_f32 v[16:17], v[16:17], v[36:37] op_sel_hi:[1,0]
	v_pk_mul_f32 v[22:23], v[22:23], v[36:37] op_sel_hi:[1,0]
	v_pk_fma_f32 v[20:21], v[34:35], v[20:21], v[4:5]
	v_pk_fma_f32 v[36:37], v[28:29], v[18:19], v[2:3]
	v_pk_fma_f32 v[18:19], v[30:31], v[16:17], v[0:1]
	v_cvt_pk_bf16_f32 v16, v20, v21
	v_pk_fma_f32 v[22:23], v[32:33], v[22:23], v[6:7]
	s_nop 0
	v_cvt_pk_bf16_f32 v17, v22, v23
	v_cvt_pk_bf16_f32 v18, v18, v19
	v_cvt_pk_bf16_f32 v19, v36, v37
	global_store_dwordx4 v[24:25], v[16:19], off offset:256
	ds_read_b32 v16, v213
	s_waitcnt lgkmcnt(0)
	v_pk_mul_f32 v[8:9], v[8:9], v[16:17] op_sel_hi:[1,0]
	v_pk_mul_f32 v[10:11], v[10:11], v[16:17] op_sel_hi:[1,0]
	v_pk_fma_f32 v[6:7], v[32:33], v[8:9], v[6:7]
	v_pk_fma_f32 v[4:5], v[34:35], v[10:11], v[4:5]
	v_pk_mul_f32 v[8:9], v[12:13], v[16:17] op_sel_hi:[1,0]
	v_pk_mul_f32 v[10:11], v[14:15], v[16:17] op_sel_hi:[1,0]
	v_pk_fma_f32 v[8:9], v[28:29], v[8:9], v[2:3]
	v_pk_fma_f32 v[2:3], v[30:31], v[10:11], v[0:1]
	v_cvt_pk_bf16_f32 v0, v4, v5
	v_cvt_pk_bf16_f32 v1, v6, v7
	s_nop 0
	v_cvt_pk_bf16_f32 v2, v2, v3
	v_cvt_pk_bf16_f32 v3, v8, v9
	global_store_dwordx4 v[26:27], v[0:3], off offset:256
	s_cbranch_vccnz .LBB0_501
	s_andn2_b64 vcc, exec, s[22:23]
	s_cbranch_vccnz .LBB0_500
	s_barrier
	s_branch .LBB0_500

.LBB0_1818:
	s_or_b64 exec, exec, s[68:69]
	s_add_u32 s0, s54, s70
	s_addc_u32 s1, s55, s71
	v_lshlrev_b64 v[0:1], 2, v[170:171]
	v_lshl_add_u64 v[114:115], s[36:37], 0, v[0:1]
	v_lshl_add_u64 v[0:1], s[0:1], 0, v[0:1]
	v_add_co_u32_e32 v2, vcc, s86, v0
	s_waitcnt vmcnt(0) lgkmcnt(0)
	s_barrier
	s_mov_b64 s[0:1], 0x22000
	v_addc_co_u32_e32 v3, vcc, 0, v1, vcc
	v_lshl_add_u64 v[120:121], v[0:1], 0, s[0:1]
	global_load_dwordx4 v[130:133], v[2:3], off
	global_load_dwordx4 v[170:173], v[120:121], off offset:16
	flat_load_dwordx4 v[174:177], v[114:115]
	flat_load_dwordx4 v[178:181], v[114:115] offset:16
	v_add_co_u32_e32 v2, vcc, s87, v0
	v_lshl_add_u64 v[122:123], v[0:1], 0, s[50:51]
	s_nop 0
	v_addc_co_u32_e32 v3, vcc, 0, v1, vcc
	global_load_dwordx4 v[4:7], v[2:3], off
	ds_read_b32 v134, v200
	global_load_dwordx4 v[0:3], v[122:123], off offset:16
	global_load_dwordx4 v[228:231], v[120:121], off offset:512
	global_load_dwordx4 v[232:235], v[120:121], off offset:528
	global_load_dwordx4 v[236:239], v[114:115], off offset:512
	global_load_dwordx4 v[240:243], v[114:115], off offset:528
	global_load_dwordx4 v[248:251], v[122:123], off offset:512
	global_load_dwordx4 v[252:255], v[122:123], off offset:528
	v_lshl_add_u64 v[128:129], s[46:47], 0, v[168:169]
	v_lshl_add_u64 v[128:129], v[128:129], 0, v[112:113]
	v_add_u32_e32 v168, s61, v192
	s_waitcnt lgkmcnt(0)
	v_pk_mul_f32 v[142:143], v[142:143], v[134:135] op_sel_hi:[1,0]
	v_pk_mul_f32 v[140:141], v[140:141], v[134:135] op_sel_hi:[1,0]
	v_pk_mul_f32 v[138:139], v[138:139], v[134:135] op_sel_hi:[1,0]
	v_pk_mul_f32 v[134:135], v[136:137], v[134:135] op_sel_hi:[1,0]
	v_ashrrev_i32_e32 v169, 31, v168
	v_add_u32_e32 v182, s61, v193
	v_ashrrev_i32_e32 v183, 31, v182
	v_add_u32_e32 v184, s61, v194
	v_ashrrev_i32_e32 v185, 31, v184
	s_andn2_b64 vcc, exec, s[10:11]
	s_mov_b64 s[0:1], -1
	s_waitcnt vmcnt(0)
	v_pk_add_f32 v[132:133], v[132:133], 1.0 op_sel_hi:[1,0]
	v_pk_add_f32 v[130:131], v[130:131], 1.0 op_sel_hi:[1,0]
	v_pk_add_f32 v[170:171], v[170:171], 1.0 op_sel_hi:[1,0]
	v_pk_add_f32 v[136:137], v[172:173], 1.0 op_sel_hi:[1,0]
	v_pk_mul_f32 v[172:173], v[176:177], v[132:133]
	v_pk_mul_f32 v[174:175], v[174:175], v[130:131]
	v_pk_mul_f32 v[170:171], v[178:179], v[170:171]
	v_pk_mul_f32 v[136:137], v[180:181], v[136:137]
	v_pk_fma_f32 v[132:133], v[172:173], v[142:143], v[6:7]
	v_pk_fma_f32 v[130:131], v[174:175], v[140:141], v[4:5]
	v_pk_fma_f32 v[134:135], v[170:171], v[134:135], v[0:1]
	v_pk_fma_f32 v[138:139], v[136:137], v[138:139], v[2:3]
	v_cvt_pk_bf16_f32 v130, v130, v131
	v_cvt_pk_bf16_f32 v131, v132, v133
	v_cvt_pk_bf16_f32 v132, v134, v135
	s_nop 0
	v_cvt_pk_bf16_f32 v133, v138, v139
	ds_read_b32 v134, v201
	global_store_dwordx4 v[128:129], v[130:133], off
	s_waitcnt lgkmcnt(0)
	v_pk_mul_f32 v[138:139], v[148:149], v[134:135] op_sel_hi:[1,0]
	v_pk_mul_f32 v[130:131], v[144:145], v[134:135] op_sel_hi:[1,0]
	v_pk_mul_f32 v[132:133], v[146:147], v[134:135] op_sel_hi:[1,0]
	v_pk_mul_f32 v[134:135], v[150:151], v[134:135] op_sel_hi:[1,0]
	v_pk_fma_f32 v[132:133], v[174:175], v[132:133], v[4:5]
	v_pk_fma_f32 v[138:139], v[136:137], v[138:139], v[2:3]
	v_pk_fma_f32 v[134:135], v[170:171], v[134:135], v[0:1]
	v_pk_fma_f32 v[130:131], v[172:173], v[130:131], v[6:7]
	v_cvt_pk_bf16_f32 v132, v132, v133
	s_nop 0
	v_cvt_pk_bf16_f32 v133, v130, v131
	v_cvt_pk_bf16_f32 v134, v134, v135
	v_cvt_pk_bf16_f32 v135, v138, v139
	ds_read_b32 v138, v202
	v_lshlrev_b64 v[130:131], 11, v[168:169]
	v_lshl_add_u64 v[130:131], s[46:47], 0, v[130:131]
	v_lshl_add_u64 v[130:131], v[130:131], 0, v[112:113]
	global_store_dwordx4 v[130:131], v[132:135], off
	s_waitcnt lgkmcnt(0)
	v_pk_mul_f32 v[94:95], v[94:95], v[138:139] op_sel_hi:[1,0]
	v_pk_mul_f32 v[92:93], v[92:93], v[138:139] op_sel_hi:[1,0]
	v_pk_mul_f32 v[88:89], v[88:89], v[138:139] op_sel_hi:[1,0]
	v_pk_mul_f32 v[90:91], v[90:91], v[138:139] op_sel_hi:[1,0]
	v_pk_fma_f32 v[94:95], v[172:173], v[94:95], v[6:7]
	v_pk_fma_f32 v[92:93], v[174:175], v[92:93], v[4:5]
	v_pk_fma_f32 v[88:89], v[170:171], v[88:89], v[0:1]
	v_pk_fma_f32 v[90:91], v[136:137], v[90:91], v[2:3]
	v_cvt_pk_bf16_f32 v92, v92, v93
	v_cvt_pk_bf16_f32 v93, v94, v95
	v_cvt_pk_bf16_f32 v94, v88, v89
	s_nop 0
	v_cvt_pk_bf16_f32 v95, v90, v91
	ds_read_b32 v88, v203
	v_lshlrev_b64 v[90:91], 11, v[182:183]
	v_lshl_add_u64 v[90:91], s[46:47], 0, v[90:91]
	v_lshl_add_u64 v[90:91], v[90:91], 0, v[112:113]
	global_store_dwordx4 v[90:91], v[92:95], off
	s_waitcnt lgkmcnt(0)
	s_nop 0
	v_pk_mul_f32 v[92:93], v[96:97], v[88:89] op_sel_hi:[1,0]
	v_pk_mul_f32 v[94:95], v[98:99], v[88:89] op_sel_hi:[1,0]
	v_pk_mul_f32 v[96:97], v[100:101], v[88:89] op_sel_hi:[1,0]
	v_pk_mul_f32 v[88:89], v[102:103], v[88:89] op_sel_hi:[1,0]
	v_pk_fma_f32 v[98:99], v[172:173], v[92:93], v[6:7]
	v_pk_fma_f32 v[92:93], v[174:175], v[94:95], v[4:5]
	v_pk_fma_f32 v[96:97], v[136:137], v[96:97], v[2:3]
	v_pk_fma_f32 v[88:89], v[170:171], v[88:89], v[0:1]
	v_cvt_pk_bf16_f32 v92, v92, v93
	v_cvt_pk_bf16_f32 v93, v98, v99
	s_nop 0
	v_cvt_pk_bf16_f32 v94, v88, v89
	v_cvt_pk_bf16_f32 v95, v96, v97
	ds_read_b32 v96, v204
	v_lshlrev_b64 v[88:89], 11, v[184:185]
	v_lshl_add_u64 v[88:89], s[46:47], 0, v[88:89]
	v_lshl_add_u64 v[88:89], v[88:89], 0, v[112:113]
	global_store_dwordx4 v[88:89], v[92:95], off
	s_waitcnt lgkmcnt(0)
	v_pk_mul_f32 v[62:63], v[62:63], v[96:97] op_sel_hi:[1,0]
	v_pk_mul_f32 v[60:61], v[60:61], v[96:97] op_sel_hi:[1,0]
	v_pk_mul_f32 v[56:57], v[56:57], v[96:97] op_sel_hi:[1,0]
	v_pk_mul_f32 v[58:59], v[58:59], v[96:97] op_sel_hi:[1,0]
	v_pk_fma_f32 v[62:63], v[172:173], v[62:63], v[6:7]
	v_pk_fma_f32 v[60:61], v[174:175], v[60:61], v[4:5]
	v_pk_fma_f32 v[56:57], v[170:171], v[56:57], v[0:1]
	v_pk_fma_f32 v[92:93], v[136:137], v[58:59], v[2:3]
	v_cvt_pk_bf16_f32 v58, v60, v61
	v_cvt_pk_bf16_f32 v59, v62, v63
	v_cvt_pk_bf16_f32 v60, v56, v57
	v_add_u32_e32 v56, s61, v195
	v_cvt_pk_bf16_f32 v61, v92, v93
	ds_read_b32 v62, v205
	v_ashrrev_i32_e32 v57, 31, v56
	v_lshlrev_b64 v[56:57], 11, v[56:57]
	v_lshl_add_u64 v[56:57], s[46:47], 0, v[56:57]
	v_lshl_add_u64 v[56:57], v[56:57], 0, v[112:113]
	global_store_dwordx4 v[56:57], v[58:61], off
	s_waitcnt lgkmcnt(0)
	s_nop 0
	v_pk_mul_f32 v[58:59], v[64:65], v[62:63] op_sel_hi:[1,0]
	v_pk_mul_f32 v[60:61], v[66:67], v[62:63] op_sel_hi:[1,0]
	v_pk_mul_f32 v[64:65], v[68:69], v[62:63] op_sel_hi:[1,0]
	v_pk_mul_f32 v[62:63], v[70:71], v[62:63] op_sel_hi:[1,0]
	v_pk_fma_f32 v[60:61], v[174:175], v[60:61], v[4:5]
	v_pk_fma_f32 v[64:65], v[136:137], v[64:65], v[2:3]
	v_pk_fma_f32 v[62:63], v[170:171], v[62:63], v[0:1]
	v_pk_fma_f32 v[58:59], v[172:173], v[58:59], v[6:7]
	v_cvt_pk_bf16_f32 v60, v60, v61
	s_nop 0
	v_cvt_pk_bf16_f32 v61, v58, v59
	v_cvt_pk_bf16_f32 v62, v62, v63
	v_cvt_pk_bf16_f32 v63, v64, v65
	ds_read_b32 v64, v206
	v_add_u32_e32 v58, s61, v196
	v_ashrrev_i32_e32 v59, 31, v58
	v_lshlrev_b64 v[58:59], 11, v[58:59]
	v_lshl_add_u64 v[58:59], s[46:47], 0, v[58:59]
	s_waitcnt lgkmcnt(0)
	v_pk_mul_f32 v[30:31], v[30:31], v[64:65] op_sel_hi:[1,0]
	v_pk_mul_f32 v[28:29], v[28:29], v[64:65] op_sel_hi:[1,0]
	v_pk_mul_f32 v[24:25], v[24:25], v[64:65] op_sel_hi:[1,0]
	v_lshl_add_u64 v[58:59], v[58:59], 0, v[112:113]
	v_pk_fma_f32 v[30:31], v[172:173], v[30:31], v[6:7]
	v_pk_fma_f32 v[28:29], v[174:175], v[28:29], v[4:5]
	v_pk_mul_f32 v[26:27], v[26:27], v[64:65] op_sel_hi:[1,0]
	v_pk_fma_f32 v[24:25], v[170:171], v[24:25], v[0:1]
	global_store_dwordx4 v[58:59], v[60:63], off
	s_nop 1
	v_pk_fma_f32 v[60:61], v[136:137], v[26:27], v[2:3]
	v_cvt_pk_bf16_f32 v26, v28, v29
	v_cvt_pk_bf16_f32 v27, v30, v31
	v_cvt_pk_bf16_f32 v28, v24, v25
	v_add_u32_e32 v24, s61, v197
	v_cvt_pk_bf16_f32 v29, v60, v61
	ds_read_b32 v30, v207
	v_ashrrev_i32_e32 v25, 31, v24
	v_lshlrev_b64 v[24:25], 11, v[24:25]
	v_lshl_add_u64 v[24:25], s[46:47], 0, v[24:25]
	v_lshl_add_u64 v[24:25], v[24:25], 0, v[112:113]
	global_store_dwordx4 v[24:25], v[26:29], off
	s_waitcnt lgkmcnt(0)
	s_nop 0
	v_pk_mul_f32 v[26:27], v[32:33], v[30:31] op_sel_hi:[1,0]
	v_pk_mul_f32 v[28:29], v[34:35], v[30:31] op_sel_hi:[1,0]
	v_pk_fma_f32 v[6:7], v[172:173], v[26:27], v[6:7]
	v_pk_fma_f32 v[4:5], v[174:175], v[28:29], v[4:5]
	v_pk_mul_f32 v[26:27], v[36:37], v[30:31] op_sel_hi:[1,0]
	v_pk_mul_f32 v[28:29], v[38:39], v[30:31] op_sel_hi:[1,0]
	v_pk_fma_f32 v[26:27], v[136:137], v[26:27], v[2:3]
	v_pk_fma_f32 v[2:3], v[170:171], v[28:29], v[0:1]
	v_cvt_pk_bf16_f32 v0, v4, v5
	v_add_u32_e32 v4, s61, v198
	v_ashrrev_i32_e32 v5, 31, v4
	v_lshlrev_b64 v[4:5], 11, v[4:5]
	v_lshl_add_u64 v[4:5], s[46:47], 0, v[4:5]
	v_lshl_add_u64 v[4:5], v[4:5], 0, v[112:113]
	v_cvt_pk_bf16_f32 v1, v6, v7
	v_cvt_pk_bf16_f32 v2, v2, v3
	v_cvt_pk_bf16_f32 v3, v26, v27
	global_store_dwordx4 v[4:5], v[0:3], off
	s_nop 1
	v_mov_b32_e32 v26, v228
	v_mov_b32_e32 v27, v229
	v_mov_b32_e32 v28, v230
	v_mov_b32_e32 v29, v231
	v_mov_b32_e32 v30, v232
	v_mov_b32_e32 v31, v233
	v_mov_b32_e32 v32, v234
	v_mov_b32_e32 v33, v235
	v_mov_b32_e32 v34, v236
	v_mov_b32_e32 v35, v237
	v_mov_b32_e32 v36, v238
	v_mov_b32_e32 v37, v239
	v_mov_b32_e32 v60, v240
	v_mov_b32_e32 v61, v241
	v_mov_b32_e32 v62, v242
	v_mov_b32_e32 v63, v243
	v_mov_b32_e32 v64, v248
	v_mov_b32_e32 v65, v249
	v_mov_b32_e32 v66, v250
	v_mov_b32_e32 v67, v251
	v_mov_b32_e32 v0, v252
	v_mov_b32_e32 v1, v253
	v_mov_b32_e32 v2, v254
	v_mov_b32_e32 v3, v255
	ds_read_b32 v6, v200
	s_waitcnt lgkmcnt(0)
	v_pk_mul_f32 v[38:39], v[126:127], v[6:7] op_sel_hi:[1,0]
	v_pk_mul_f32 v[68:69], v[124:125], v[6:7] op_sel_hi:[1,0]
	v_pk_mul_f32 v[70:71], v[118:119], v[6:7] op_sel_hi:[1,0]
	v_pk_mul_f32 v[6:7], v[116:117], v[6:7] op_sel_hi:[1,0]
	s_nop 0
	v_pk_add_f32 v[28:29], v[28:29], 1.0 op_sel_hi:[1,0]
	v_pk_add_f32 v[26:27], v[26:27], 1.0 op_sel_hi:[1,0]
	v_pk_add_f32 v[30:31], v[30:31], 1.0 op_sel_hi:[1,0]
	v_pk_add_f32 v[32:33], v[32:33], 1.0 op_sel_hi:[1,0]
	v_pk_mul_f32 v[36:37], v[36:37], v[28:29]
	v_pk_mul_f32 v[34:35], v[34:35], v[26:27]
	v_pk_mul_f32 v[30:31], v[60:61], v[30:31]
	v_pk_mul_f32 v[32:33], v[62:63], v[32:33]
	v_pk_fma_f32 v[28:29], v[36:37], v[38:39], v[66:67]
	v_pk_fma_f32 v[26:27], v[34:35], v[68:69], v[64:65]
	v_pk_fma_f32 v[6:7], v[30:31], v[6:7], v[0:1]
	v_pk_fma_f32 v[38:39], v[32:33], v[70:71], v[2:3]
	v_cvt_pk_bf16_f32 v26, v26, v27
	v_cvt_pk_bf16_f32 v27, v28, v29
	v_cvt_pk_bf16_f32 v28, v6, v7
	s_nop 0
	v_cvt_pk_bf16_f32 v29, v38, v39
	ds_read_b32 v6, v201
	global_store_dwordx4 v[128:129], v[26:29], off offset:256
	s_waitcnt lgkmcnt(0)
	v_pk_mul_f32 v[38:39], v[108:109], v[6:7] op_sel_hi:[1,0]
	v_pk_mul_f32 v[26:27], v[104:105], v[6:7] op_sel_hi:[1,0]
	v_pk_mul_f32 v[28:29], v[106:107], v[6:7] op_sel_hi:[1,0]
	v_pk_mul_f32 v[6:7], v[110:111], v[6:7] op_sel_hi:[1,0]
	v_pk_fma_f32 v[60:61], v[36:37], v[26:27], v[66:67]
	v_pk_fma_f32 v[26:27], v[34:35], v[28:29], v[64:65]
	v_pk_fma_f32 v[6:7], v[30:31], v[6:7], v[0:1]
	v_pk_fma_f32 v[38:39], v[32:33], v[38:39], v[2:3]
	v_cvt_pk_bf16_f32 v26, v26, v27
	v_cvt_pk_bf16_f32 v27, v60, v61
	v_cvt_pk_bf16_f32 v28, v6, v7
	s_nop 0
	v_cvt_pk_bf16_f32 v29, v38, v39
	ds_read_b32 v6, v202
	global_store_dwordx4 v[130:131], v[26:29], off offset:256
	s_waitcnt lgkmcnt(0)
	v_pk_mul_f32 v[38:39], v[82:83], v[6:7] op_sel_hi:[1,0]
	v_pk_mul_f32 v[26:27], v[86:87], v[6:7] op_sel_hi:[1,0]
	v_pk_mul_f32 v[28:29], v[84:85], v[6:7] op_sel_hi:[1,0]
	v_pk_mul_f32 v[6:7], v[80:81], v[6:7] op_sel_hi:[1,0]
	v_pk_fma_f32 v[60:61], v[36:37], v[26:27], v[66:67]
	v_pk_fma_f32 v[26:27], v[34:35], v[28:29], v[64:65]
	v_pk_fma_f32 v[6:7], v[30:31], v[6:7], v[0:1]
	v_pk_fma_f32 v[38:39], v[32:33], v[38:39], v[2:3]
	v_cvt_pk_bf16_f32 v26, v26, v27
	v_cvt_pk_bf16_f32 v27, v60, v61
	v_cvt_pk_bf16_f32 v28, v6, v7
	s_nop 0
	v_cvt_pk_bf16_f32 v29, v38, v39
	ds_read_b32 v6, v203
	global_store_dwordx4 v[90:91], v[26:29], off offset:256
	s_waitcnt lgkmcnt(0)
	s_nop 0
	v_pk_mul_f32 v[26:27], v[72:73], v[6:7] op_sel_hi:[1,0]
	v_pk_mul_f32 v[28:29], v[74:75], v[6:7] op_sel_hi:[1,0]
	v_pk_fma_f32 v[38:39], v[36:37], v[26:27], v[66:67]
	v_pk_fma_f32 v[26:27], v[34:35], v[28:29], v[64:65]
	v_pk_mul_f32 v[28:29], v[76:77], v[6:7] op_sel_hi:[1,0]
	v_pk_mul_f32 v[6:7], v[78:79], v[6:7] op_sel_hi:[1,0]
	v_pk_fma_f32 v[60:61], v[32:33], v[28:29], v[2:3]
	v_pk_fma_f32 v[6:7], v[30:31], v[6:7], v[0:1]
	v_cvt_pk_bf16_f32 v26, v26, v27
	v_cvt_pk_bf16_f32 v27, v38, v39
	s_nop 0
	v_cvt_pk_bf16_f32 v28, v6, v7
	v_cvt_pk_bf16_f32 v29, v60, v61
	ds_read_b32 v6, v204
	global_store_dwordx4 v[88:89], v[26:29], off offset:256
	s_waitcnt lgkmcnt(0)
	s_nop 0
	v_pk_mul_f32 v[26:27], v[54:55], v[6:7] op_sel_hi:[1,0]
	v_pk_mul_f32 v[28:29], v[52:53], v[6:7] op_sel_hi:[1,0]
	v_pk_fma_f32 v[38:39], v[36:37], v[26:27], v[66:67]
	v_pk_fma_f32 v[26:27], v[34:35], v[28:29], v[64:65]
	v_pk_mul_f32 v[28:29], v[50:51], v[6:7] op_sel_hi:[1,0]
	v_pk_mul_f32 v[6:7], v[48:49], v[6:7] op_sel_hi:[1,0]
	v_pk_fma_f32 v[48:49], v[32:33], v[28:29], v[2:3]
	v_pk_fma_f32 v[6:7], v[30:31], v[6:7], v[0:1]
	v_cvt_pk_bf16_f32 v26, v26, v27
	v_cvt_pk_bf16_f32 v27, v38, v39
	s_nop 0
	v_cvt_pk_bf16_f32 v28, v6, v7
	v_cvt_pk_bf16_f32 v29, v48, v49
	ds_read_b32 v6, v205
	global_store_dwordx4 v[56:57], v[26:29], off offset:256
	s_waitcnt lgkmcnt(0)
	s_nop 0
	v_pk_mul_f32 v[26:27], v[40:41], v[6:7] op_sel_hi:[1,0]
	v_pk_mul_f32 v[28:29], v[42:43], v[6:7] op_sel_hi:[1,0]
	v_pk_fma_f32 v[38:39], v[36:37], v[26:27], v[66:67]
	v_pk_fma_f32 v[26:27], v[34:35], v[28:29], v[64:65]
	v_pk_mul_f32 v[28:29], v[44:45], v[6:7] op_sel_hi:[1,0]
	v_pk_mul_f32 v[6:7], v[46:47], v[6:7] op_sel_hi:[1,0]
	v_pk_fma_f32 v[40:41], v[32:33], v[28:29], v[2:3]
	v_pk_fma_f32 v[6:7], v[30:31], v[6:7], v[0:1]
	v_cvt_pk_bf16_f32 v26, v26, v27
	v_cvt_pk_bf16_f32 v27, v38, v39
	s_nop 0
	v_cvt_pk_bf16_f32 v28, v6, v7
	v_cvt_pk_bf16_f32 v29, v40, v41
	ds_read_b32 v6, v206
	global_store_dwordx4 v[58:59], v[26:29], off offset:256
	s_waitcnt lgkmcnt(0)
	v_pk_mul_f32 v[22:23], v[22:23], v[6:7] op_sel_hi:[1,0]
	v_pk_mul_f32 v[20:21], v[20:21], v[6:7] op_sel_hi:[1,0]
	v_pk_mul_f32 v[18:19], v[18:19], v[6:7] op_sel_hi:[1,0]
	v_pk_mul_f32 v[6:7], v[16:17], v[6:7] op_sel_hi:[1,0]
	v_pk_fma_f32 v[22:23], v[36:37], v[22:23], v[66:67]
	v_pk_fma_f32 v[6:7], v[30:31], v[6:7], v[0:1]
	v_pk_fma_f32 v[20:21], v[34:35], v[20:21], v[64:65]
	v_pk_fma_f32 v[26:27], v[32:33], v[18:19], v[2:3]
	v_cvt_pk_bf16_f32 v16, v20, v21
	v_cvt_pk_bf16_f32 v17, v22, v23
	v_cvt_pk_bf16_f32 v18, v6, v7
	s_nop 0
	v_cvt_pk_bf16_f32 v19, v26, v27
	ds_read_b32 v6, v207
	global_store_dwordx4 v[24:25], v[16:19], off offset:256
	s_waitcnt lgkmcnt(0)
	v_pk_mul_f32 v[8:9], v[8:9], v[6:7] op_sel_hi:[1,0]
	v_pk_mul_f32 v[10:11], v[10:11], v[6:7] op_sel_hi:[1,0]
	v_pk_mul_f32 v[12:13], v[12:13], v[6:7] op_sel_hi:[1,0]
	v_pk_mul_f32 v[6:7], v[14:15], v[6:7] op_sel_hi:[1,0]
	v_pk_fma_f32 v[12:13], v[32:33], v[12:13], v[2:3]
	v_pk_fma_f32 v[2:3], v[30:31], v[6:7], v[0:1]
	v_pk_fma_f32 v[8:9], v[36:37], v[8:9], v[66:67]
	v_pk_fma_f32 v[10:11], v[34:35], v[10:11], v[64:65]
	s_nop 0
	v_cvt_pk_bf16_f32 v0, v10, v11
	v_cvt_pk_bf16_f32 v1, v8, v9
	v_cvt_pk_bf16_f32 v2, v2, v3
	v_cvt_pk_bf16_f32 v3, v12, v13
	global_store_dwordx4 v[4:5], v[0:3], off offset:256
	s_cbranch_vccnz .LBB0_1782
	s_andn2_b64 vcc, exec, s[14:15]
	s_cbranch_vccnz .LBB0_1781
	s_barrier
	s_branch .LBB0_1781

.LBB0_1981:
	s_or_b64 exec, exec, s[50:51]
	v_lshlrev_b64 v[114:115], 2, v[168:169]
	s_waitcnt vmcnt(0) lgkmcnt(0)
	s_barrier
	v_lshl_add_u64 v[112:113], s[12:13], 0, v[114:115]
	flat_load_dwordx4 v[4:7], v[112:113]
	flat_load_dwordx4 v[0:3], v[112:113] offset:16
	global_load_dwordx4 v[238:241], v[112:113], off offset:512
	global_load_dwordx4 v[242:245], v[112:113], off offset:528
	v_add_u32_e32 v116, s41, v178
	v_add_u32_e32 v118, s41, v179
	v_ashrrev_i32_e32 v117, 31, v116
	v_ashrrev_i32_e32 v119, 31, v118
	v_add_u32_e32 v168, s41, v180
	v_lshlrev_b64 v[116:117], 12, v[116:117]
	v_lshlrev_b64 v[118:119], 12, v[118:119]
	v_lshlrev_b64 v[124:125], 12, v[170:171]
	v_ashrrev_i32_e32 v169, 31, v168
	v_lshl_add_u64 v[116:117], s[52:53], 0, v[116:117]
	v_lshl_add_u64 v[118:119], s[52:53], 0, v[118:119]
	v_lshl_add_u64 v[170:171], s[52:53], 0, v[124:125]
	ds_read_b32 v134, v186
	ds_read_b32 v132, v187
	ds_read_b32 v126, v188
	ds_read_b32 v124, v189
	ds_read_b32 v172, v189
	ds_read_b32 v202, v188
	ds_read_b32 v204, v187
	ds_read_b32 v206, v186
	ds_read_b32 v208, v190
	ds_read_b32 v210, v191
	ds_read_b32 v212, v192
	ds_read_b32 v214, v193
	ds_read_b32 v216, v193
	ds_read_b32 v218, v192
	ds_read_b32 v220, v191
	ds_read_b32 v222, v190
	v_lshlrev_b64 v[168:169], 12, v[168:169]
	v_lshl_add_u64 v[224:225], v[116:117], 0, v[114:115]
	v_lshl_add_u64 v[226:227], v[118:119], 0, v[114:115]
	s_waitcnt lgkmcnt(0)
	v_pk_mul_f32 v[116:117], v[142:143], v[134:135] op_sel_hi:[1,0]
	v_pk_mul_f32 v[118:119], v[140:141], v[134:135] op_sel_hi:[1,0]
	v_lshl_add_u64 v[170:171], v[170:171], 0, v[114:115]
	v_lshl_add_u64 v[168:169], s[52:53], 0, v[168:169]
	v_pk_mul_f32 v[138:139], v[138:139], v[134:135] op_sel_hi:[1,0]
	v_pk_mul_f32 v[134:135], v[136:137], v[134:135] op_sel_hi:[1,0]
	v_pk_mul_f32 v[136:137], v[144:145], v[132:133] op_sel_hi:[1,0]
	v_pk_mul_f32 v[140:141], v[146:147], v[132:133] op_sel_hi:[1,0]
	v_pk_mul_f32 v[142:143], v[148:149], v[132:133] op_sel_hi:[1,0]
	v_pk_mul_f32 v[132:133], v[150:151], v[132:133] op_sel_hi:[1,0]
	v_pk_mul_f32 v[144:145], v[94:95], v[126:127] op_sel_hi:[1,0]
	v_pk_mul_f32 v[146:147], v[92:93], v[126:127] op_sel_hi:[1,0]
	v_pk_mul_f32 v[148:149], v[90:91], v[126:127] op_sel_hi:[1,0]
	v_pk_mul_f32 v[126:127], v[88:89], v[126:127] op_sel_hi:[1,0]
	v_pk_mul_f32 v[150:151], v[96:97], v[124:125] op_sel_hi:[1,0]
	v_pk_mul_f32 v[228:229], v[98:99], v[124:125] op_sel_hi:[1,0]
	v_pk_mul_f32 v[230:231], v[100:101], v[124:125] op_sel_hi:[1,0]
	v_pk_mul_f32 v[232:233], v[102:103], v[124:125] op_sel_hi:[1,0]
	v_pk_mul_f32 v[234:235], v[62:63], v[208:209] op_sel_hi:[1,0]
	v_pk_mul_f32 v[236:237], v[60:61], v[208:209] op_sel_hi:[1,0]
	v_lshl_add_u64 v[168:169], v[168:169], 0, v[114:115]
	v_pk_mul_f32 v[56:57], v[56:57], v[208:209] op_sel_hi:[1,0]
	v_pk_mul_f32 v[58:59], v[58:59], v[208:209] op_sel_hi:[1,0]
	v_pk_mul_f32 v[30:31], v[30:31], v[212:213] op_sel_hi:[1,0]
	v_pk_mul_f32 v[28:29], v[28:29], v[212:213] op_sel_hi:[1,0]
	v_pk_mul_f32 v[24:25], v[24:25], v[212:213] op_sel_hi:[1,0]
	v_pk_mul_f32 v[26:27], v[26:27], v[212:213] op_sel_hi:[1,0]
	v_pk_mul_f32 v[22:23], v[22:23], v[218:219] op_sel_hi:[1,0]
	v_pk_mul_f32 v[20:21], v[20:21], v[218:219] op_sel_hi:[1,0]
	v_pk_mul_f32 v[8:9], v[8:9], v[216:217] op_sel_hi:[1,0]
	v_pk_mul_f32 v[10:11], v[10:11], v[216:217] op_sel_hi:[1,0]
	v_pk_mul_f32 v[18:19], v[18:19], v[218:219] op_sel_hi:[1,0]
	v_pk_mul_f32 v[16:17], v[16:17], v[218:219] op_sel_hi:[1,0]
	s_andn2_b64 vcc, exec, s[8:9]
	s_mov_b64 s[8:9], -1
	s_waitcnt vmcnt(0)
	v_pk_fma_f32 v[62:63], v[6:7], v[116:117], 0 op_sel_hi:[1,1,0]
	v_pk_fma_f32 v[60:61], v[4:5], v[118:119], 0 op_sel_hi:[1,1,0]
	v_pk_fma_f32 v[90:91], v[2:3], v[138:139], 0 op_sel_hi:[1,1,0]
	v_pk_fma_f32 v[88:89], v[0:1], v[134:135], 0 op_sel_hi:[1,1,0]
	v_pk_fma_f32 v[94:95], v[6:7], v[136:137], 0 op_sel_hi:[1,1,0]
	v_pk_fma_f32 v[92:93], v[4:5], v[140:141], 0 op_sel_hi:[1,1,0]
	v_pk_fma_f32 v[98:99], v[2:3], v[142:143], 0 op_sel_hi:[1,1,0]
	v_pk_fma_f32 v[96:97], v[0:1], v[132:133], 0 op_sel_hi:[1,1,0]
	v_pk_fma_f32 v[102:103], v[6:7], v[144:145], 0 op_sel_hi:[1,1,0]
	v_pk_fma_f32 v[100:101], v[4:5], v[146:147], 0 op_sel_hi:[1,1,0]
	v_pk_fma_f32 v[118:119], v[2:3], v[148:149], 0 op_sel_hi:[1,1,0]
	v_pk_fma_f32 v[116:117], v[0:1], v[126:127], 0 op_sel_hi:[1,1,0]
	v_pk_fma_f32 v[126:127], v[6:7], v[150:151], 0 op_sel_hi:[1,1,0]
	v_pk_fma_f32 v[124:125], v[4:5], v[228:229], 0 op_sel_hi:[1,1,0]
	v_pk_fma_f32 v[134:135], v[2:3], v[230:231], 0 op_sel_hi:[1,1,0]
	v_pk_fma_f32 v[132:133], v[0:1], v[232:233], 0 op_sel_hi:[1,1,0]
	global_store_dwordx4 v[170:171], v[60:63], off
	global_store_dwordx4 v[170:171], v[88:91], off offset:16
	global_store_dwordx4 v[224:225], v[92:95], off
	global_store_dwordx4 v[224:225], v[96:99], off offset:16
	global_store_dwordx4 v[226:227], v[100:103], off
	global_store_dwordx4 v[226:227], v[116:119], off offset:16
	global_store_dwordx4 v[168:169], v[124:127], off
	global_store_dwordx4 v[168:169], v[132:135], off offset:16
	v_add_u32_e32 v60, s41, v181
	v_ashrrev_i32_e32 v61, 31, v60
	v_lshlrev_b64 v[60:61], 12, v[60:61]
	v_lshl_add_u64 v[60:61], s[52:53], 0, v[60:61]
	v_pk_fma_f32 v[136:137], v[6:7], v[234:235], 0 op_sel_hi:[1,1,0]
	v_pk_fma_f32 v[134:135], v[4:5], v[236:237], 0 op_sel_hi:[1,1,0]
	v_pk_fma_f32 v[56:57], v[0:1], v[56:57], 0 op_sel_hi:[1,1,0]
	v_lshl_add_u64 v[88:89], v[60:61], 0, v[114:115]
	v_pk_fma_f32 v[58:59], v[2:3], v[58:59], 0 op_sel_hi:[1,1,0]
	global_store_dwordx4 v[88:89], v[134:137], off
	global_store_dwordx4 v[88:89], v[56:59], off offset:16
	v_pk_mul_f32 v[60:61], v[66:67], v[210:211] op_sel_hi:[1,0]
	v_pk_fma_f32 v[30:31], v[6:7], v[30:31], 0 op_sel_hi:[1,1,0]
	v_pk_mul_f32 v[56:57], v[64:65], v[210:211] op_sel_hi:[1,0]
	v_pk_mul_f32 v[64:65], v[70:71], v[210:211] op_sel_hi:[1,0]
	v_pk_fma_f32 v[58:59], v[6:7], v[56:57], 0 op_sel_hi:[1,1,0]
	v_pk_fma_f32 v[56:57], v[4:5], v[60:61], 0 op_sel_hi:[1,1,0]
	v_pk_mul_f32 v[60:61], v[68:69], v[210:211] op_sel_hi:[1,0]
	v_pk_fma_f32 v[28:29], v[4:5], v[28:29], 0 op_sel_hi:[1,1,0]
	v_pk_fma_f32 v[62:63], v[2:3], v[60:61], 0 op_sel_hi:[1,1,0]
	v_pk_fma_f32 v[60:61], v[0:1], v[64:65], 0 op_sel_hi:[1,1,0]
	v_add_u32_e32 v64, s41, v182
	v_ashrrev_i32_e32 v65, 31, v64
	v_lshlrev_b64 v[64:65], 12, v[64:65]
	v_lshl_add_u64 v[64:65], s[52:53], 0, v[64:65]
	v_lshl_add_u64 v[64:65], v[64:65], 0, v[114:115]
	global_store_dwordx4 v[64:65], v[56:59], off
	global_store_dwordx4 v[64:65], v[60:63], off offset:16
	v_pk_fma_f32 v[24:25], v[0:1], v[24:25], 0 op_sel_hi:[1,1,0]
	v_add_u32_e32 v56, s41, v183
	v_ashrrev_i32_e32 v57, 31, v56
	v_lshlrev_b64 v[56:57], 12, v[56:57]
	v_lshl_add_u64 v[56:57], s[52:53], 0, v[56:57]
	v_lshl_add_u64 v[60:61], v[56:57], 0, v[114:115]
	v_pk_fma_f32 v[26:27], v[2:3], v[26:27], 0 op_sel_hi:[1,1,0]
	global_store_dwordx4 v[60:61], v[28:31], off
	global_store_dwordx4 v[60:61], v[24:27], off offset:16
	v_pk_mul_f32 v[56:57], v[110:111], v[204:205] op_sel_hi:[1,0]
	v_pk_mul_f32 v[28:29], v[128:129], v[206:207] op_sel_hi:[1,0]
	v_pk_mul_f32 v[24:25], v[32:33], v[214:215] op_sel_hi:[1,0]
	v_pk_mul_f32 v[26:27], v[34:35], v[214:215] op_sel_hi:[1,0]
	v_pk_fma_f32 v[6:7], v[6:7], v[24:25], 0 op_sel_hi:[1,1,0]
	v_pk_mul_f32 v[24:25], v[36:37], v[214:215] op_sel_hi:[1,0]
	v_pk_fma_f32 v[4:5], v[4:5], v[26:27], 0 op_sel_hi:[1,1,0]
	v_pk_fma_f32 v[2:3], v[2:3], v[24:25], 0 op_sel_hi:[1,1,0]
	v_add_u32_e32 v24, s41, v184
	v_ashrrev_i32_e32 v25, 31, v24
	v_lshlrev_b64 v[24:25], 12, v[24:25]
	v_lshl_add_u64 v[24:25], s[52:53], 0, v[24:25]
	v_pk_mul_f32 v[26:27], v[38:39], v[214:215] op_sel_hi:[1,0]
	v_lshl_add_u64 v[62:63], v[24:25], 0, v[114:115]
	v_pk_fma_f32 v[0:1], v[0:1], v[26:27], 0 op_sel_hi:[1,1,0]
	global_store_dwordx4 v[62:63], v[4:7], off
	global_store_dwordx4 v[62:63], v[0:3], off offset:16
	s_nop 1
	v_mov_b32_e32 v0, v238
	v_mov_b32_e32 v1, v239
	v_mov_b32_e32 v2, v240
	v_mov_b32_e32 v3, v241
	s_nop 0
	v_mov_b32_e32 v4, v242
	v_mov_b32_e32 v5, v243
	v_mov_b32_e32 v6, v244
	v_mov_b32_e32 v7, v245
	v_pk_mul_f32 v[24:25], v[130:131], v[206:207] op_sel_hi:[1,0]
	v_pk_mul_f32 v[32:33], v[120:121], v[206:207] op_sel_hi:[1,0]
	v_pk_mul_f32 v[30:31], v[122:123], v[206:207] op_sel_hi:[1,0]
	v_pk_mul_f32 v[34:35], v[104:105], v[204:205] op_sel_hi:[1,0]
	v_pk_mul_f32 v[36:37], v[106:107], v[204:205] op_sel_hi:[1,0]
	v_pk_mul_f32 v[38:39], v[108:109], v[204:205] op_sel_hi:[1,0]
	v_pk_mul_f32 v[58:59], v[86:87], v[202:203] op_sel_hi:[1,0]
	v_pk_mul_f32 v[66:67], v[84:85], v[202:203] op_sel_hi:[1,0]
	s_waitcnt lgkmcnt(0)
	v_pk_fma_f32 v[26:27], v[2:3], v[24:25], 0 op_sel_hi:[1,1,0]
	v_pk_fma_f32 v[24:25], v[0:1], v[28:29], 0 op_sel_hi:[1,1,0]
	v_pk_fma_f32 v[28:29], v[4:5], v[32:33], 0 op_sel_hi:[1,1,0]
	v_pk_fma_f32 v[30:31], v[6:7], v[30:31], 0 op_sel_hi:[1,1,0]
	v_pk_fma_f32 v[34:35], v[2:3], v[34:35], 0 op_sel_hi:[1,1,0]
	v_pk_fma_f32 v[32:33], v[0:1], v[36:37], 0 op_sel_hi:[1,1,0]
	v_pk_fma_f32 v[38:39], v[6:7], v[38:39], 0 op_sel_hi:[1,1,0]
	v_pk_fma_f32 v[36:37], v[4:5], v[56:57], 0 op_sel_hi:[1,1,0]
	global_store_dwordx4 v[170:171], v[24:27], off offset:512
	global_store_dwordx4 v[170:171], v[28:31], off offset:528
	global_store_dwordx4 v[224:225], v[32:35], off offset:512
	global_store_dwordx4 v[224:225], v[36:39], off offset:528
	v_pk_mul_f32 v[24:25], v[82:83], v[202:203] op_sel_hi:[1,0]
	v_pk_mul_f32 v[28:29], v[80:81], v[202:203] op_sel_hi:[1,0]
	v_pk_fma_f32 v[58:59], v[2:3], v[58:59], 0 op_sel_hi:[1,1,0]
	v_pk_fma_f32 v[56:57], v[0:1], v[66:67], 0 op_sel_hi:[1,1,0]
	v_pk_fma_f32 v[26:27], v[6:7], v[24:25], 0 op_sel_hi:[1,1,0]
	v_pk_fma_f32 v[24:25], v[4:5], v[28:29], 0 op_sel_hi:[1,1,0]
	global_store_dwordx4 v[226:227], v[56:59], off offset:512
	global_store_dwordx4 v[226:227], v[24:27], off offset:528
	v_pk_mul_f32 v[28:29], v[74:75], v[172:173] op_sel_hi:[1,0]
	v_pk_mul_f32 v[32:33], v[78:79], v[172:173] op_sel_hi:[1,0]
	v_pk_mul_f32 v[24:25], v[72:73], v[172:173] op_sel_hi:[1,0]
	v_pk_fma_f32 v[22:23], v[2:3], v[22:23], 0 op_sel_hi:[1,1,0]
	v_pk_fma_f32 v[26:27], v[2:3], v[24:25], 0 op_sel_hi:[1,1,0]
	v_pk_fma_f32 v[24:25], v[0:1], v[28:29], 0 op_sel_hi:[1,1,0]
	v_pk_mul_f32 v[28:29], v[76:77], v[172:173] op_sel_hi:[1,0]
	v_pk_fma_f32 v[20:21], v[0:1], v[20:21], 0 op_sel_hi:[1,1,0]
	v_pk_fma_f32 v[30:31], v[6:7], v[28:29], 0 op_sel_hi:[1,1,0]
	v_pk_fma_f32 v[28:29], v[4:5], v[32:33], 0 op_sel_hi:[1,1,0]
	global_store_dwordx4 v[168:169], v[24:27], off offset:512
	global_store_dwordx4 v[168:169], v[28:31], off offset:528
	v_pk_mul_f32 v[32:33], v[48:49], v[222:223] op_sel_hi:[1,0]
	v_pk_mul_f32 v[24:25], v[54:55], v[222:223] op_sel_hi:[1,0]
	v_pk_mul_f32 v[28:29], v[52:53], v[222:223] op_sel_hi:[1,0]
	v_pk_fma_f32 v[26:27], v[2:3], v[24:25], 0 op_sel_hi:[1,1,0]
	v_pk_fma_f32 v[24:25], v[0:1], v[28:29], 0 op_sel_hi:[1,1,0]
	v_pk_mul_f32 v[28:29], v[50:51], v[222:223] op_sel_hi:[1,0]
	v_pk_fma_f32 v[18:19], v[6:7], v[18:19], 0 op_sel_hi:[1,1,0]
	v_pk_fma_f32 v[30:31], v[6:7], v[28:29], 0 op_sel_hi:[1,1,0]
	v_pk_fma_f32 v[28:29], v[4:5], v[32:33], 0 op_sel_hi:[1,1,0]
	global_store_dwordx4 v[88:89], v[24:27], off offset:512
	global_store_dwordx4 v[88:89], v[28:31], off offset:528
	v_pk_mul_f32 v[32:33], v[46:47], v[220:221] op_sel_hi:[1,0]
	v_pk_mul_f32 v[24:25], v[40:41], v[220:221] op_sel_hi:[1,0]
	v_pk_mul_f32 v[28:29], v[42:43], v[220:221] op_sel_hi:[1,0]
	v_pk_fma_f32 v[26:27], v[2:3], v[24:25], 0 op_sel_hi:[1,1,0]
	v_pk_fma_f32 v[24:25], v[0:1], v[28:29], 0 op_sel_hi:[1,1,0]
	v_pk_mul_f32 v[28:29], v[44:45], v[220:221] op_sel_hi:[1,0]
	v_pk_fma_f32 v[2:3], v[2:3], v[8:9], 0 op_sel_hi:[1,1,0]
	v_pk_fma_f32 v[0:1], v[0:1], v[10:11], 0 op_sel_hi:[1,1,0]
	v_pk_mul_f32 v[8:9], v[12:13], v[216:217] op_sel_hi:[1,0]
	v_pk_mul_f32 v[10:11], v[14:15], v[216:217] op_sel_hi:[1,0]
	v_pk_fma_f32 v[30:31], v[6:7], v[28:29], 0 op_sel_hi:[1,1,0]
	v_pk_fma_f32 v[28:29], v[4:5], v[32:33], 0 op_sel_hi:[1,1,0]
	global_store_dwordx4 v[64:65], v[24:27], off offset:512
	global_store_dwordx4 v[64:65], v[28:31], off offset:528
	v_pk_fma_f32 v[16:17], v[4:5], v[16:17], 0 op_sel_hi:[1,1,0]
	global_store_dwordx4 v[60:61], v[20:23], off offset:512
	global_store_dwordx4 v[60:61], v[16:19], off offset:528
	v_pk_fma_f32 v[6:7], v[6:7], v[8:9], 0 op_sel_hi:[1,1,0]
	v_pk_fma_f32 v[4:5], v[4:5], v[10:11], 0 op_sel_hi:[1,1,0]
	global_store_dwordx4 v[62:63], v[0:3], off offset:512
	global_store_dwordx4 v[62:63], v[4:7], off offset:528
	s_cbranch_vccnz .LBB0_1945
	s_andn2_b64 vcc, exec, s[14:15]
	s_cbranch_vccnz .LBB0_1944
	s_barrier
	s_branch .LBB0_1944

	.amdhsa_kernel _Z14fwd_megakernel4Args
		.amdhsa_group_segment_fixed_size 0
		.amdhsa_private_segment_fixed_size 0
		.amdhsa_kernarg_size 544
		.amdhsa_user_sgpr_count 2
		.amdhsa_user_sgpr_dispatch_ptr 0
		.amdhsa_user_sgpr_queue_ptr 0
		.amdhsa_user_sgpr_kernarg_segment_ptr 1
		.amdhsa_user_sgpr_dispatch_id 0
		.amdhsa_user_sgpr_kernarg_preload_length 0
		.amdhsa_user_sgpr_kernarg_preload_offset 0
		.amdhsa_user_sgpr_private_segment_size 0
		.amdhsa_uses_dynamic_stack 0
		.amdhsa_enable_private_segment 0
		.amdhsa_system_sgpr_workgroup_id_x 1
		.amdhsa_system_sgpr_workgroup_id_y 0
		.amdhsa_system_sgpr_workgroup_id_z 0
		.amdhsa_system_sgpr_workgroup_info 0
		.amdhsa_system_vgpr_workitem_id 2
		.amdhsa_next_free_vgpr 256
		.amdhsa_next_free_sgpr 100
		.amdhsa_accum_offset 256
		.amdhsa_reserve_vcc 1
		.amdhsa_float_round_mode_32 0
		.amdhsa_float_round_mode_16_64 0
		.amdhsa_float_denorm_mode_32 3
		.amdhsa_float_denorm_mode_16_64 3
		.amdhsa_dx10_clamp 1
		.amdhsa_ieee_mode 1
		.amdhsa_fp16_overflow 0
		.amdhsa_tg_split 0
		.amdhsa_exception_fp_ieee_invalid_op 0
		.amdhsa_exception_fp_denorm_src 0
		.amdhsa_exception_fp_ieee_div_zero 0
		.amdhsa_exception_fp_ieee_overflow 0
		.amdhsa_exception_fp_ieee_underflow 0
		.amdhsa_exception_fp_ieee_inexact 0
		.amdhsa_exception_int_div_zero 0
	.end_amdhsa_kernel

amdhsa.kernels:
  - .agpr_count:     0
    .args:
      - .offset:         0
        .size:           288
        .value_kind:     by_value
      - .offset:         288
        .size:           4
        .value_kind:     hidden_block_count_x
      - .offset:         292
        .size:           4
        .value_kind:     hidden_block_count_y
      - .offset:         296
        .size:           4
        .value_kind:     hidden_block_count_z
      - .offset:         300
        .size:           2
        .value_kind:     hidden_group_size_x
      - .offset:         302
        .size:           2
        .value_kind:     hidden_group_size_y
      - .offset:         304
        .size:           2
        .value_kind:     hidden_group_size_z
      - .offset:         306
        .size:           2
        .value_kind:     hidden_remainder_x
      - .offset:         308
        .size:           2
        .value_kind:     hidden_remainder_y
      - .offset:         310
        .size:           2
        .value_kind:     hidden_remainder_z
      - .offset:         328
        .size:           8
        .value_kind:     hidden_global_offset_x
      - .offset:         336
        .size:           8
        .value_kind:     hidden_global_offset_y
      - .offset:         344
        .size:           8
        .value_kind:     hidden_global_offset_z
      - .offset:         352
        .size:           2
        .value_kind:     hidden_grid_dims
      - .offset:         376
        .size:           8
        .value_kind:     hidden_multigrid_sync_arg
      - .offset:         408
        .size:           4
        .value_kind:     hidden_dynamic_lds_size
    .group_segment_fixed_size: 0
    .kernarg_segment_align: 8
    .kernarg_segment_size: 544
    .language:       OpenCL C
    .language_version:
      - 2
      - 0
    .max_flat_workgroup_size: 512
    .name:           _Z14fwd_megakernel4Args
    .private_segment_fixed_size: 0
    .sgpr_count:     106
    .sgpr_spill_count: 27
    .symbol:         _Z14fwd_megakernel4Args.kd
    .uniform_work_group_size: 1
    .uses_dynamic_stack: false
    .vgpr_count:     256
    .vgpr_spill_count: 0
    .wavefront_size: 64
